# stack: DPP butterflies in GEMM epilogue, de-serialized transposed weight loads in prep, hand-scheduled DSA tile loop, VALU counting in top-k bit loop
# speedup vs baseline: 1.0821x; 1.0521x over previous
.LBB0_46:
	v_lshrrev_b32_e32 v3, 6, v0
	v_lshrrev_b32_e32 v8, 6, v1
	v_add_lshl_u32 v5, v3, s12, 6
	v_add_lshl_u32 v4, v8, s13, 6
	v_or_b32_e32 v36, v5, v106
	v_or_b32_e32 v4, v4, v33
	v_lshl_add_u64 v[6:7], v[36:37], 2, s[76:77]
	v_mov_b32_e32 v5, v37
	v_lshl_add_u64 v[4:5], v[4:5], 2, s[76:77]
	global_load_dword v146, v[6:7], off
	global_load_dword v147, v[4:5], off
	v_mad_u64_u32 v[4:5], s[28:29], v3, s46, v[32:33]
	v_mad_u64_u32 v[6:7], s[28:29], v8, s46, v[32:33]
	v_add_u32_e32 v3, 0x200, v1
	v_lshrrev_b32_e32 v3, 6, v3
	v_add_u32_e32 v2, -4, v2
	v_cmp_eq_u32_e32 vcc, 0, v2
	s_or_b64 s[26:27], vcc, s[26:27]
	v_mov_b32_e32 v170, v4
	v_mov_b32_e32 v171, v6
	v_add_u32_e32 v4, 0x200, v0
	v_lshrrev_b32_e32 v8, 6, v4
	v_add_lshl_u32 v5, v8, s12, 6
	v_add_lshl_u32 v4, v3, s13, 6
	v_or_b32_e32 v36, v5, v106
	v_or_b32_e32 v4, v4, v33
	v_lshl_add_u64 v[6:7], v[36:37], 2, s[76:77]
	v_mov_b32_e32 v5, v37
	v_lshl_add_u64 v[4:5], v[4:5], 2, s[76:77]
	global_load_dword v148, v[6:7], off
	global_load_dword v149, v[4:5], off
	v_mad_u64_u32 v[4:5], s[28:29], v8, s46, v[32:33]
	v_mad_u64_u32 v[6:7], s[28:29], v3, s46, v[32:33]
	v_add_u32_e32 v3, 0x400, v1
	v_lshrrev_b32_e32 v3, 6, v3
	v_mov_b32_e32 v172, v4
	v_mov_b32_e32 v173, v6
	v_add_u32_e32 v4, 0x400, v0
	v_lshrrev_b32_e32 v8, 6, v4
	v_add_lshl_u32 v5, v8, s12, 6
	v_add_lshl_u32 v4, v3, s13, 6
	v_or_b32_e32 v36, v5, v106
	v_or_b32_e32 v4, v4, v33
	v_lshl_add_u64 v[6:7], v[36:37], 2, s[76:77]
	v_mov_b32_e32 v5, v37
	v_lshl_add_u64 v[4:5], v[4:5], 2, s[76:77]
	global_load_dword v150, v[6:7], off
	global_load_dword v151, v[4:5], off
	v_mad_u64_u32 v[4:5], s[28:29], v8, s46, v[32:33]
	v_mad_u64_u32 v[6:7], s[28:29], v3, s46, v[32:33]
	v_add_u32_e32 v3, 0x600, v1
	v_lshrrev_b32_e32 v3, 6, v3
	v_add_u32_e32 v1, 0x800, v1
	v_mov_b32_e32 v174, v4
	v_mov_b32_e32 v175, v6
	v_add_u32_e32 v4, 0x600, v0
	v_lshrrev_b32_e32 v8, 6, v4
	v_add_lshl_u32 v5, v8, s12, 6
	v_add_lshl_u32 v4, v3, s13, 6
	v_or_b32_e32 v36, v5, v106
	v_or_b32_e32 v4, v4, v33
	v_lshl_add_u64 v[6:7], v[36:37], 2, s[76:77]
	v_mov_b32_e32 v5, v37
	v_lshl_add_u64 v[4:5], v[4:5], 2, s[76:77]
	global_load_dword v152, v[6:7], off
	global_load_dword v153, v[4:5], off
	v_mad_u64_u32 v[4:5], s[28:29], v8, s46, v[32:33]
	v_add_u32_e32 v0, 0x800, v0
	v_mad_u64_u32 v[6:7], s[28:29], v3, s46, v[32:33]
	v_mov_b32_e32 v176, v4
	v_mov_b32_e32 v177, v6
	s_waitcnt vmcnt(7)
	ds_write_b32 v170, v146
	s_waitcnt vmcnt(6)
	ds_write_b32 v171, v147
	s_waitcnt vmcnt(5)
	ds_write_b32 v172, v148
	s_waitcnt vmcnt(4)
	ds_write_b32 v173, v149
	s_waitcnt vmcnt(3)
	ds_write_b32 v174, v150
	s_waitcnt vmcnt(2)
	ds_write_b32 v175, v151
	s_waitcnt vmcnt(1)
	ds_write_b32 v176, v152
	s_waitcnt vmcnt(0)
	ds_write_b32 v177, v153
	s_andn2_b64 exec, exec, s[26:27]
	s_cbranch_execnz .LBB0_46
	s_or_b64 exec, exec, s[26:27]
	s_and_saveexec_b64 s[26:27], s[6:7]
	s_cbranch_execz .LBB0_50
	s_mov_b64 s[28:29], 0
	v_mov_b32_e32 v2, v77

.LBB0_62:
	v_lshrrev_b32_e32 v3, 6, v0
	v_lshrrev_b32_e32 v8, 6, v1
	v_add_lshl_u32 v5, v3, s12, 6
	v_add_lshl_u32 v4, v8, s13, 6
	v_or_b32_e32 v36, v5, v106
	v_or_b32_e32 v4, v4, v33
	v_lshl_add_u64 v[6:7], v[36:37], 2, s[68:69]
	v_mov_b32_e32 v5, v37
	v_lshl_add_u64 v[4:5], v[4:5], 2, s[68:69]
	global_load_dword v146, v[6:7], off
	global_load_dword v147, v[4:5], off
	v_mad_u64_u32 v[4:5], s[28:29], v3, s46, v[32:33]
	v_mad_u64_u32 v[6:7], s[28:29], v8, s46, v[32:33]
	v_add_u32_e32 v3, 0x200, v1
	v_lshrrev_b32_e32 v3, 6, v3
	v_add_u32_e32 v2, -4, v2
	v_cmp_eq_u32_e32 vcc, 0, v2
	s_or_b64 s[26:27], vcc, s[26:27]
	v_mov_b32_e32 v170, v4
	v_mov_b32_e32 v171, v6
	v_add_u32_e32 v4, 0x200, v0
	v_lshrrev_b32_e32 v8, 6, v4
	v_add_lshl_u32 v5, v8, s12, 6
	v_add_lshl_u32 v4, v3, s13, 6
	v_or_b32_e32 v36, v5, v106
	v_or_b32_e32 v4, v4, v33
	v_lshl_add_u64 v[6:7], v[36:37], 2, s[68:69]
	v_mov_b32_e32 v5, v37
	v_lshl_add_u64 v[4:5], v[4:5], 2, s[68:69]
	global_load_dword v148, v[6:7], off
	global_load_dword v149, v[4:5], off
	v_mad_u64_u32 v[4:5], s[28:29], v8, s46, v[32:33]
	v_mad_u64_u32 v[6:7], s[28:29], v3, s46, v[32:33]
	v_add_u32_e32 v3, 0x400, v1
	v_lshrrev_b32_e32 v3, 6, v3
	v_mov_b32_e32 v172, v4
	v_mov_b32_e32 v173, v6
	v_add_u32_e32 v4, 0x400, v0
	v_lshrrev_b32_e32 v8, 6, v4
	v_add_lshl_u32 v5, v8, s12, 6
	v_add_lshl_u32 v4, v3, s13, 6
	v_or_b32_e32 v36, v5, v106
	v_or_b32_e32 v4, v4, v33
	v_lshl_add_u64 v[6:7], v[36:37], 2, s[68:69]
	v_mov_b32_e32 v5, v37
	v_lshl_add_u64 v[4:5], v[4:5], 2, s[68:69]
	global_load_dword v150, v[6:7], off
	global_load_dword v151, v[4:5], off
	v_mad_u64_u32 v[4:5], s[28:29], v8, s46, v[32:33]
	v_mad_u64_u32 v[6:7], s[28:29], v3, s46, v[32:33]
	v_add_u32_e32 v3, 0x600, v1
	v_lshrrev_b32_e32 v3, 6, v3
	v_add_u32_e32 v1, 0x800, v1
	v_mov_b32_e32 v174, v4
	v_mov_b32_e32 v175, v6
	v_add_u32_e32 v4, 0x600, v0
	v_lshrrev_b32_e32 v8, 6, v4
	v_add_lshl_u32 v5, v8, s12, 6
	v_add_lshl_u32 v4, v3, s13, 6
	v_or_b32_e32 v36, v5, v106
	v_or_b32_e32 v4, v4, v33
	v_lshl_add_u64 v[6:7], v[36:37], 2, s[68:69]
	v_mov_b32_e32 v5, v37
	v_lshl_add_u64 v[4:5], v[4:5], 2, s[68:69]
	global_load_dword v152, v[6:7], off
	global_load_dword v153, v[4:5], off
	v_mad_u64_u32 v[4:5], s[28:29], v8, s46, v[32:33]
	v_add_u32_e32 v0, 0x800, v0
	v_mad_u64_u32 v[6:7], s[28:29], v3, s46, v[32:33]
	v_mov_b32_e32 v176, v4
	v_mov_b32_e32 v177, v6
	s_waitcnt vmcnt(7)
	ds_write_b32 v170, v146
	s_waitcnt vmcnt(6)
	ds_write_b32 v171, v147
	s_waitcnt vmcnt(5)
	ds_write_b32 v172, v148
	s_waitcnt vmcnt(4)
	ds_write_b32 v173, v149
	s_waitcnt vmcnt(3)
	ds_write_b32 v174, v150
	s_waitcnt vmcnt(2)
	ds_write_b32 v175, v151
	s_waitcnt vmcnt(1)
	ds_write_b32 v176, v152
	s_waitcnt vmcnt(0)
	ds_write_b32 v177, v153
	s_andn2_b64 exec, exec, s[26:27]
	s_cbranch_execnz .LBB0_62
	s_or_b64 exec, exec, s[26:27]
	s_and_saveexec_b64 s[26:27], s[6:7]
	s_cbranch_execz .LBB0_66
	s_mov_b64 s[28:29], 0
	v_mov_b32_e32 v2, v77

.LBB0_77:
	v_lshrrev_b32_e32 v5, 6, v2
	v_lshrrev_b32_e32 v10, 6, v3
	v_add_lshl_u32 v7, v5, s26, 8
	v_add_lshl_u32 v6, v10, s28, 8
	v_or_b32_e32 v36, v0, v7
	v_or_b32_e32 v6, v1, v6
	v_lshl_add_u64 v[8:9], v[36:37], 2, s[72:73]
	v_mov_b32_e32 v7, v37
	v_lshl_add_u64 v[6:7], v[6:7], 2, s[72:73]
	global_load_dword v146, v[8:9], off
	global_load_dword v147, v[6:7], off
	v_mad_u64_u32 v[6:7], s[16:17], v5, s46, v[32:33]
	v_mad_u64_u32 v[8:9], s[16:17], v10, s46, v[32:33]
	v_add_u32_e32 v5, 0x200, v3
	v_lshrrev_b32_e32 v5, 6, v5
	v_add_u32_e32 v4, -4, v4
	v_cmp_eq_u32_e32 vcc, 0, v4
	s_or_b64 s[14:15], vcc, s[14:15]
	v_mov_b32_e32 v170, v6
	v_mov_b32_e32 v171, v8
	v_add_u32_e32 v6, 0x200, v2
	v_lshrrev_b32_e32 v10, 6, v6
	v_add_lshl_u32 v7, v10, s26, 8
	v_add_lshl_u32 v6, v5, s28, 8
	v_or_b32_e32 v36, v0, v7
	v_or_b32_e32 v6, v1, v6
	v_lshl_add_u64 v[8:9], v[36:37], 2, s[72:73]
	v_mov_b32_e32 v7, v37
	v_lshl_add_u64 v[6:7], v[6:7], 2, s[72:73]
	global_load_dword v148, v[8:9], off
	global_load_dword v149, v[6:7], off
	v_mad_u64_u32 v[6:7], s[16:17], v10, s46, v[32:33]
	v_mad_u64_u32 v[8:9], s[16:17], v5, s46, v[32:33]
	v_add_u32_e32 v5, 0x400, v3
	v_lshrrev_b32_e32 v5, 6, v5
	v_mov_b32_e32 v172, v6
	v_mov_b32_e32 v173, v8
	v_add_u32_e32 v6, 0x400, v2
	v_lshrrev_b32_e32 v10, 6, v6
	v_add_lshl_u32 v7, v10, s26, 8
	v_add_lshl_u32 v6, v5, s28, 8
	v_or_b32_e32 v36, v0, v7
	v_or_b32_e32 v6, v1, v6
	v_lshl_add_u64 v[8:9], v[36:37], 2, s[72:73]
	v_mov_b32_e32 v7, v37
	v_lshl_add_u64 v[6:7], v[6:7], 2, s[72:73]
	global_load_dword v150, v[8:9], off
	global_load_dword v151, v[6:7], off
	v_mad_u64_u32 v[6:7], s[16:17], v10, s46, v[32:33]
	v_mad_u64_u32 v[8:9], s[16:17], v5, s46, v[32:33]
	v_add_u32_e32 v5, 0x600, v3
	v_lshrrev_b32_e32 v5, 6, v5
	v_add_u32_e32 v3, 0x800, v3
	v_mov_b32_e32 v174, v6
	v_mov_b32_e32 v175, v8
	v_add_u32_e32 v6, 0x600, v2
	v_lshrrev_b32_e32 v10, 6, v6
	v_add_lshl_u32 v7, v10, s26, 8
	v_add_lshl_u32 v6, v5, s28, 8
	v_or_b32_e32 v36, v0, v7
	v_or_b32_e32 v6, v1, v6
	v_lshl_add_u64 v[8:9], v[36:37], 2, s[72:73]
	v_mov_b32_e32 v7, v37
	v_lshl_add_u64 v[6:7], v[6:7], 2, s[72:73]
	global_load_dword v152, v[8:9], off
	global_load_dword v153, v[6:7], off
	v_mad_u64_u32 v[6:7], s[16:17], v10, s46, v[32:33]
	v_add_u32_e32 v2, 0x800, v2
	v_mad_u64_u32 v[8:9], s[16:17], v5, s46, v[32:33]
	v_mov_b32_e32 v176, v6
	v_mov_b32_e32 v177, v8
	s_waitcnt vmcnt(7)
	ds_write_b32 v170, v146
	s_waitcnt vmcnt(6)
	ds_write_b32 v171, v147
	s_waitcnt vmcnt(5)
	ds_write_b32 v172, v148
	s_waitcnt vmcnt(4)
	ds_write_b32 v173, v149
	s_waitcnt vmcnt(3)
	ds_write_b32 v174, v150
	s_waitcnt vmcnt(2)
	ds_write_b32 v175, v151
	s_waitcnt vmcnt(1)
	ds_write_b32 v176, v152
	s_waitcnt vmcnt(0)
	ds_write_b32 v177, v153
	s_andn2_b64 exec, exec, s[14:15]
	s_cbranch_execnz .LBB0_77
	s_or_b64 exec, exec, s[14:15]
	s_and_saveexec_b64 s[14:15], s[6:7]
	s_cbranch_execz .LBB0_81
	s_mov_b64 s[16:17], 0
	v_mov_b32_e32 v4, v77

.LBB0_94:
	v_lshrrev_b32_e32 v5, 6, v2
	v_lshrrev_b32_e32 v10, 6, v3
	v_add_lshl_u32 v7, v5, s26, 8
	v_add_lshl_u32 v6, v10, s28, 8
	v_or_b32_e32 v36, v0, v7
	v_or_b32_e32 v6, v1, v6
	v_lshl_add_u64 v[8:9], v[36:37], 2, s[64:65]
	v_mov_b32_e32 v7, v37
	v_lshl_add_u64 v[6:7], v[6:7], 2, s[64:65]
	global_load_dword v146, v[8:9], off
	global_load_dword v147, v[6:7], off
	v_mad_u64_u32 v[6:7], s[16:17], v5, s46, v[32:33]
	v_mad_u64_u32 v[8:9], s[16:17], v10, s46, v[32:33]
	v_add_u32_e32 v5, 0x200, v3
	v_lshrrev_b32_e32 v5, 6, v5
	v_add_u32_e32 v4, -4, v4
	v_cmp_eq_u32_e32 vcc, 0, v4
	s_or_b64 s[14:15], vcc, s[14:15]
	v_mov_b32_e32 v170, v6
	v_mov_b32_e32 v171, v8
	v_add_u32_e32 v6, 0x200, v2
	v_lshrrev_b32_e32 v10, 6, v6
	v_add_lshl_u32 v7, v10, s26, 8
	v_add_lshl_u32 v6, v5, s28, 8
	v_or_b32_e32 v36, v0, v7
	v_or_b32_e32 v6, v1, v6
	v_lshl_add_u64 v[8:9], v[36:37], 2, s[64:65]
	v_mov_b32_e32 v7, v37
	v_lshl_add_u64 v[6:7], v[6:7], 2, s[64:65]
	global_load_dword v148, v[8:9], off
	global_load_dword v149, v[6:7], off
	v_mad_u64_u32 v[6:7], s[16:17], v10, s46, v[32:33]
	v_mad_u64_u32 v[8:9], s[16:17], v5, s46, v[32:33]
	v_add_u32_e32 v5, 0x400, v3
	v_lshrrev_b32_e32 v5, 6, v5
	v_mov_b32_e32 v172, v6
	v_mov_b32_e32 v173, v8
	v_add_u32_e32 v6, 0x400, v2
	v_lshrrev_b32_e32 v10, 6, v6
	v_add_lshl_u32 v7, v10, s26, 8
	v_add_lshl_u32 v6, v5, s28, 8
	v_or_b32_e32 v36, v0, v7
	v_or_b32_e32 v6, v1, v6
	v_lshl_add_u64 v[8:9], v[36:37], 2, s[64:65]
	v_mov_b32_e32 v7, v37
	v_lshl_add_u64 v[6:7], v[6:7], 2, s[64:65]
	global_load_dword v150, v[8:9], off
	global_load_dword v151, v[6:7], off
	v_mad_u64_u32 v[6:7], s[16:17], v10, s46, v[32:33]
	v_mad_u64_u32 v[8:9], s[16:17], v5, s46, v[32:33]
	v_add_u32_e32 v5, 0x600, v3
	v_lshrrev_b32_e32 v5, 6, v5
	v_add_u32_e32 v3, 0x800, v3
	v_mov_b32_e32 v174, v6
	v_mov_b32_e32 v175, v8
	v_add_u32_e32 v6, 0x600, v2
	v_lshrrev_b32_e32 v10, 6, v6
	v_add_lshl_u32 v7, v10, s26, 8
	v_add_lshl_u32 v6, v5, s28, 8
	v_or_b32_e32 v36, v0, v7
	v_or_b32_e32 v6, v1, v6
	v_lshl_add_u64 v[8:9], v[36:37], 2, s[64:65]
	v_mov_b32_e32 v7, v37
	v_lshl_add_u64 v[6:7], v[6:7], 2, s[64:65]
	global_load_dword v152, v[8:9], off
	global_load_dword v153, v[6:7], off
	v_mad_u64_u32 v[6:7], s[16:17], v10, s46, v[32:33]
	v_add_u32_e32 v2, 0x800, v2
	v_mad_u64_u32 v[8:9], s[16:17], v5, s46, v[32:33]
	v_mov_b32_e32 v176, v6
	v_mov_b32_e32 v177, v8
	s_waitcnt vmcnt(7)
	ds_write_b32 v170, v146
	s_waitcnt vmcnt(6)
	ds_write_b32 v171, v147
	s_waitcnt vmcnt(5)
	ds_write_b32 v172, v148
	s_waitcnt vmcnt(4)
	ds_write_b32 v173, v149
	s_waitcnt vmcnt(3)
	ds_write_b32 v174, v150
	s_waitcnt vmcnt(2)
	ds_write_b32 v175, v151
	s_waitcnt vmcnt(1)
	ds_write_b32 v176, v152
	s_waitcnt vmcnt(0)
	ds_write_b32 v177, v153
	s_andn2_b64 exec, exec, s[14:15]
	s_cbranch_execnz .LBB0_94
	s_or_b64 exec, exec, s[14:15]
	s_and_saveexec_b64 s[14:15], s[6:7]
	s_cbranch_execz .LBB0_98
	s_mov_b64 s[16:17], 0
	v_mov_b32_e32 v4, v77

.LBB0_111:
	v_lshrrev_b32_e32 v5, 6, v2
	v_lshrrev_b32_e32 v10, 6, v3
	v_add_lshl_u32 v7, v5, s18, 10
	v_add_lshl_u32 v6, v10, s27, 10
	v_or_b32_e32 v36, v0, v7
	v_or_b32_e32 v6, v1, v6
	v_lshl_add_u64 v[8:9], v[36:37], 2, s[86:87]
	v_mov_b32_e32 v7, v37
	v_lshl_add_u64 v[6:7], v[6:7], 2, s[86:87]
	global_load_dword v146, v[8:9], off
	global_load_dword v147, v[6:7], off
	v_mad_u64_u32 v[6:7], s[16:17], v5, s46, v[32:33]
	v_mad_u64_u32 v[8:9], s[16:17], v10, s46, v[32:33]
	v_add_u32_e32 v5, 0x200, v3
	v_lshrrev_b32_e32 v5, 6, v5
	v_add_u32_e32 v4, -4, v4
	v_cmp_eq_u32_e32 vcc, 0, v4
	s_or_b64 s[14:15], vcc, s[14:15]
	v_mov_b32_e32 v170, v6
	v_mov_b32_e32 v171, v8
	v_add_u32_e32 v6, 0x200, v2
	v_lshrrev_b32_e32 v10, 6, v6
	v_add_lshl_u32 v7, v10, s18, 10
	v_add_lshl_u32 v6, v5, s27, 10
	v_or_b32_e32 v36, v0, v7
	v_or_b32_e32 v6, v1, v6
	v_lshl_add_u64 v[8:9], v[36:37], 2, s[86:87]
	v_mov_b32_e32 v7, v37
	v_lshl_add_u64 v[6:7], v[6:7], 2, s[86:87]
	global_load_dword v148, v[8:9], off
	global_load_dword v149, v[6:7], off
	v_mad_u64_u32 v[6:7], s[16:17], v10, s46, v[32:33]
	v_mad_u64_u32 v[8:9], s[16:17], v5, s46, v[32:33]
	v_add_u32_e32 v5, 0x400, v3
	v_lshrrev_b32_e32 v5, 6, v5
	v_mov_b32_e32 v172, v6
	v_mov_b32_e32 v173, v8
	v_add_u32_e32 v6, 0x400, v2
	v_lshrrev_b32_e32 v10, 6, v6
	v_add_lshl_u32 v7, v10, s18, 10
	v_add_lshl_u32 v6, v5, s27, 10
	v_or_b32_e32 v36, v0, v7
	v_or_b32_e32 v6, v1, v6
	v_lshl_add_u64 v[8:9], v[36:37], 2, s[86:87]
	v_mov_b32_e32 v7, v37
	v_lshl_add_u64 v[6:7], v[6:7], 2, s[86:87]
	global_load_dword v150, v[8:9], off
	global_load_dword v151, v[6:7], off
	v_mad_u64_u32 v[6:7], s[16:17], v10, s46, v[32:33]
	v_mad_u64_u32 v[8:9], s[16:17], v5, s46, v[32:33]
	v_add_u32_e32 v5, 0x600, v3
	v_lshrrev_b32_e32 v5, 6, v5
	v_add_u32_e32 v3, 0x800, v3
	v_mov_b32_e32 v174, v6
	v_mov_b32_e32 v175, v8
	v_add_u32_e32 v6, 0x600, v2
	v_lshrrev_b32_e32 v10, 6, v6
	v_add_lshl_u32 v7, v10, s18, 10
	v_add_lshl_u32 v6, v5, s27, 10
	v_or_b32_e32 v36, v0, v7
	v_or_b32_e32 v6, v1, v6
	v_lshl_add_u64 v[8:9], v[36:37], 2, s[86:87]
	v_mov_b32_e32 v7, v37
	v_lshl_add_u64 v[6:7], v[6:7], 2, s[86:87]
	global_load_dword v152, v[8:9], off
	global_load_dword v153, v[6:7], off
	v_mad_u64_u32 v[6:7], s[16:17], v10, s46, v[32:33]
	v_add_u32_e32 v2, 0x800, v2
	v_mad_u64_u32 v[8:9], s[16:17], v5, s46, v[32:33]
	v_mov_b32_e32 v176, v6
	v_mov_b32_e32 v177, v8
	s_waitcnt vmcnt(7)
	ds_write_b32 v170, v146
	s_waitcnt vmcnt(6)
	ds_write_b32 v171, v147
	s_waitcnt vmcnt(5)
	ds_write_b32 v172, v148
	s_waitcnt vmcnt(4)
	ds_write_b32 v173, v149
	s_waitcnt vmcnt(3)
	ds_write_b32 v174, v150
	s_waitcnt vmcnt(2)
	ds_write_b32 v175, v151
	s_waitcnt vmcnt(1)
	ds_write_b32 v176, v152
	s_waitcnt vmcnt(0)
	ds_write_b32 v177, v153
	s_andn2_b64 exec, exec, s[14:15]
	s_cbranch_execnz .LBB0_111
	s_or_b64 exec, exec, s[14:15]
	s_and_saveexec_b64 s[14:15], s[6:7]
	s_cbranch_execz .LBB0_115
	s_mov_b64 s[16:17], 0
	v_mov_b32_e32 v4, v77

.LBB0_126:
	s_andn2_b64 vcc, exec, s[12:13]
	s_cbranch_vccnz .LBB0_132
	s_add_i32 s12, s2, 0xf800
	s_bfe_u32 s13, s12, 0xf0001
	s_mul_i32 s13, s13, 0x97b5
	s_lshr_b32 s16, s13, 20
	s_mul_i32 s13, s16, 54
	s_sub_i32 s12, s12, s13
	s_lshl_b32 s13, s12, 6
	s_and_b32 s17, s13, 0xffc0
	s_and_b32 s12, s12, 0xffff
	v_or_b32_e32 v0, s17, v106
	s_cmp_lt_u32 s12, 20
	v_add_u32_e32 v1, 24, v0
	s_cselect_b64 vcc, -1, 0
	s_cmp_gt_u32 s12, 44
	v_cndmask_b32_e32 v1, v1, v0, vcc
	s_cselect_b64 vcc, -1, 0
	s_cmp_lt_u32 s12, 53
	s_movk_i32 s12, 0xd5c
	v_add_u32_e32 v2, 0xfffffe00, v0
	v_cmp_gt_u32_e64 s[12:13], s12, v0
	v_add_u32_e32 v3, 0xfffff7c0, v0
	v_add_u32_e32 v4, 28, v0
	v_cndmask_b32_e64 v2, -1, v2, s[12:13]
	s_movk_i32 s12, 0xd58
	v_cmp_gt_u32_e64 s[12:13], s12, v0
	s_mov_b64 s[14:15], 0
	s_nop 0
	v_cndmask_b32_e64 v0, v2, v3, s[12:13]
	s_cselect_b64 s[12:13], -1, 0
	v_cndmask_b32_e64 v0, v0, v4, s[12:13]
	v_cndmask_b32_e32 v0, v1, v0, vcc
	s_mul_i32 s12, s16, 0x35700
	v_cmp_lt_i32_e32 vcc, -1, v0
	v_add3_u32 v36, v84, v0, s12
	v_mov_b32_e32 v0, v86
	v_mov_b32_e32 v1, v81
	v_readlane_b32 s60, v250, 8
	v_readlane_b32 s64, v250, 12
	v_readlane_b32 s65, v250, 13
	v_readlane_b32 s61, v250, 9
	v_readlane_b32 s62, v250, 10
	v_readlane_b32 s63, v250, 11
	v_readlane_b32 s66, v250, 14
	v_readlane_b32 s67, v250, 15
	v_readlane_b32 s68, v250, 16
	v_readlane_b32 s69, v250, 17
	v_readlane_b32 s70, v250, 18
	v_readlane_b32 s71, v250, 19
	v_readlane_b32 s72, v250, 20
	v_readlane_b32 s73, v250, 21
	v_readlane_b32 s74, v250, 22
	v_readlane_b32 s75, v250, 23
	v_mov_b32_e32 v130, 0
	v_mov_b32_e32 v131, 0
	v_mov_b32_e32 v132, 0
	v_mov_b32_e32 v133, 0
	v_mov_b32_e32 v134, 0
	v_mov_b32_e32 v135, 0
	v_mov_b32_e32 v136, 0
	v_mov_b32_e32 v137, 0
	v_mov_b32_e32 v138, 0
	v_mov_b32_e32 v139, 0
	v_mov_b32_e32 v140, 0
	v_mov_b32_e32 v141, 0
	v_mov_b32_e32 v142, 0
	v_mov_b32_e32 v143, 0
	v_mov_b32_e32 v144, 0
	v_mov_b32_e32 v145, 0
	s_and_saveexec_b64 s[12:13], vcc
	v_lshl_add_u64 v[2:3], v[36:37], 2, s[64:65]
	global_load_dword v130, v[2:3], off
	v_add_u32_e32 v36, 0x3570, v36
	v_lshl_add_u64 v[2:3], v[36:37], 2, s[64:65]
	global_load_dword v131, v[2:3], off
	v_add_u32_e32 v36, 0x3570, v36
	v_lshl_add_u64 v[2:3], v[36:37], 2, s[64:65]
	global_load_dword v132, v[2:3], off
	v_add_u32_e32 v36, 0x3570, v36
	v_lshl_add_u64 v[2:3], v[36:37], 2, s[64:65]
	global_load_dword v133, v[2:3], off
	v_add_u32_e32 v36, 0x3570, v36
	v_lshl_add_u64 v[2:3], v[36:37], 2, s[64:65]
	global_load_dword v134, v[2:3], off
	v_add_u32_e32 v36, 0x3570, v36
	v_lshl_add_u64 v[2:3], v[36:37], 2, s[64:65]
	global_load_dword v135, v[2:3], off
	v_add_u32_e32 v36, 0x3570, v36
	v_lshl_add_u64 v[2:3], v[36:37], 2, s[64:65]
	global_load_dword v136, v[2:3], off
	v_add_u32_e32 v36, 0x3570, v36
	v_lshl_add_u64 v[2:3], v[36:37], 2, s[64:65]
	global_load_dword v137, v[2:3], off
	v_add_u32_e32 v36, 0x3570, v36
	v_lshl_add_u64 v[2:3], v[36:37], 2, s[64:65]
	global_load_dword v138, v[2:3], off
	v_add_u32_e32 v36, 0x3570, v36
	v_lshl_add_u64 v[2:3], v[36:37], 2, s[64:65]
	global_load_dword v139, v[2:3], off
	v_add_u32_e32 v36, 0x3570, v36
	v_lshl_add_u64 v[2:3], v[36:37], 2, s[64:65]
	global_load_dword v140, v[2:3], off
	v_add_u32_e32 v36, 0x3570, v36
	v_lshl_add_u64 v[2:3], v[36:37], 2, s[64:65]
	global_load_dword v141, v[2:3], off
	v_add_u32_e32 v36, 0x3570, v36
	v_lshl_add_u64 v[2:3], v[36:37], 2, s[64:65]
	global_load_dword v142, v[2:3], off
	v_add_u32_e32 v36, 0x3570, v36
	v_lshl_add_u64 v[2:3], v[36:37], 2, s[64:65]
	global_load_dword v143, v[2:3], off
	v_add_u32_e32 v36, 0x3570, v36
	v_lshl_add_u64 v[2:3], v[36:37], 2, s[64:65]
	global_load_dword v144, v[2:3], off
	v_add_u32_e32 v36, 0x3570, v36
	v_lshl_add_u64 v[2:3], v[36:37], 2, s[64:65]
	global_load_dword v145, v[2:3], off
	s_or_b64 exec, exec, s[12:13]
	s_waitcnt vmcnt(15)
	ds_write_b32 v0, v130
	s_waitcnt vmcnt(14)
	ds_write_b32 v0, v131 offset:1040
	s_waitcnt vmcnt(13)
	ds_write_b32 v0, v132 offset:2080
	s_waitcnt vmcnt(12)
	ds_write_b32 v0, v133 offset:3120
	s_waitcnt vmcnt(11)
	ds_write_b32 v0, v134 offset:4160
	s_waitcnt vmcnt(10)
	ds_write_b32 v0, v135 offset:5200
	s_waitcnt vmcnt(9)
	ds_write_b32 v0, v136 offset:6240
	s_waitcnt vmcnt(8)
	ds_write_b32 v0, v137 offset:7280
	s_waitcnt vmcnt(7)
	ds_write_b32 v0, v138 offset:8320
	s_waitcnt vmcnt(6)
	ds_write_b32 v0, v139 offset:9360
	s_waitcnt vmcnt(5)
	ds_write_b32 v0, v140 offset:10400
	s_waitcnt vmcnt(4)
	ds_write_b32 v0, v141 offset:11440
	s_waitcnt vmcnt(3)
	ds_write_b32 v0, v142 offset:12480
	s_waitcnt vmcnt(2)
	ds_write_b32 v0, v143 offset:13520
	s_waitcnt vmcnt(1)
	ds_write_b32 v0, v144 offset:14560
	s_waitcnt vmcnt(0)
	ds_write_b32 v0, v145 offset:15600
.LBB0_131:
	s_waitcnt lgkmcnt(0)
	s_barrier
	ds_read2_b32 v[0:1], v69 offset1:65
	ds_read2_b32 v[2:3], v69 offset0:130 offset1:195
	v_add_u32_e32 v4, 0x400, v69
	s_waitcnt lgkmcnt(1)
	v_cvt_pk_bf16_f32 v0, v0, v1
	s_waitcnt lgkmcnt(0)
	v_cvt_pk_bf16_f32 v1, v2, v3
	ds_read2_b32 v[2:3], v4 offset0:4 offset1:69
	ds_read2_b32 v[4:5], v4 offset0:134 offset1:199
	v_add_u32_e32 v6, 0x800, v69
	s_waitcnt lgkmcnt(1)
	v_cvt_pk_bf16_f32 v2, v2, v3
	s_waitcnt lgkmcnt(0)
	v_cvt_pk_bf16_f32 v3, v4, v5
	ds_read2_b32 v[4:5], v6 offset0:8 offset1:73
	ds_read2_b32 v[6:7], v6 offset0:138 offset1:203
	v_add_u32_e32 v8, 0xc00, v69
	s_waitcnt lgkmcnt(1)
	v_cvt_pk_bf16_f32 v4, v4, v5
	s_waitcnt lgkmcnt(0)
	v_cvt_pk_bf16_f32 v5, v6, v7
	ds_read2_b32 v[6:7], v8 offset0:12 offset1:77
	ds_read2_b32 v[8:9], v8 offset0:142 offset1:207
	v_add_lshl_u32 v36, v68, s17, 11
	s_waitcnt lgkmcnt(1)
	v_cvt_pk_bf16_f32 v6, v6, v7
	s_waitcnt lgkmcnt(0)
	v_cvt_pk_bf16_f32 v7, v8, v9
	v_lshl_add_u64 v[8:9], s[92:93], 0, v[36:37]
	s_lshl_b32 s18, s16, 7
	v_lshl_add_u64 v[8:9], v[8:9], 0, s[18:19]
	v_lshlrev_b32_e32 v36, 1, v34
	v_lshl_add_u64 v[8:9], v[8:9], 0, v[36:37]
	global_store_dwordx4 v[8:9], v[0:3], off
	global_store_dwordx4 v[8:9], v[4:7], off offset:16
	s_barrier

.LBB0_305:
	s_and_b64 vcc, exec, s[6:7]
	s_cbranch_vccz .LBB0_444
	v_or_b32_e32 v206, 1, v64
	v_lshlrev_b32_e32 v65, 5, v64
	s_mov_b32 s6, 0x1f980
	v_lshlrev_b32_e32 v70, 5, v206
	v_and_or_b32 v65, v65, s6, v108
	v_and_or_b32 v70, v70, s41, v108
	v_readlane_b32 s56, v250, 24
	v_lshlrev_b32_e32 v65, 3, v65
	v_lshlrev_b32_e32 v70, 3, v70
	v_readlane_b32 s70, v250, 38
	v_readlane_b32 s71, v250, 39
	v_or_b32_e32 v198, 2, v64
	v_or_b32_e32 v192, 3, v64
	s_nop 2
	global_load_dwordx2 v[208:209], v65, s[70:71]
	global_load_dwordx2 v[204:205], v65, s[70:71] offset:128
	global_load_dwordx2 v[86:87], v70, s[70:71]
	global_load_dwordx2 v[84:85], v70, s[70:71] offset:128
	v_lshlrev_b32_e32 v65, 5, v198
	v_lshlrev_b32_e32 v70, 5, v192
	v_and_or_b32 v65, v65, s42, v108
	v_and_or_b32 v70, v70, s43, v108
	v_lshlrev_b32_e32 v65, 3, v65
	v_lshlrev_b32_e32 v70, 3, v70
	v_or_b32_e32 v186, 16, v64
	v_or_b32_e32 v180, 17, v64
	global_load_dwordx2 v[202:203], v65, s[70:71]
	global_load_dwordx2 v[200:201], v65, s[70:71] offset:128
	global_load_dwordx2 v[196:197], v70, s[70:71]
	global_load_dwordx2 v[194:195], v70, s[70:71] offset:128
	v_lshlrev_b32_e32 v65, 5, v186
	v_lshlrev_b32_e32 v70, 5, v180
	v_and_or_b32 v65, v65, s44, v108
	v_and_or_b32 v70, v70, s41, v108
	v_lshlrev_b32_e32 v65, 3, v65
	v_lshlrev_b32_e32 v70, 3, v70
	v_or_b32_e32 v174, 18, v64
	v_or_b32_e32 v168, 19, v64
	global_load_dwordx2 v[190:191], v65, s[70:71]
	global_load_dwordx2 v[188:189], v65, s[70:71] offset:128
	global_load_dwordx2 v[184:185], v70, s[70:71]
	global_load_dwordx2 v[182:183], v70, s[70:71] offset:128
	v_lshlrev_b32_e32 v65, 5, v174
	v_lshlrev_b32_e32 v70, 5, v168
	v_and_or_b32 v65, v65, s42, v108
	v_and_or_b32 v70, v70, s43, v108
	v_lshlrev_b32_e32 v65, 3, v65
	v_lshlrev_b32_e32 v70, 3, v70
	v_or_b32_e32 v162, 32, v64
	v_or_b32_e32 v156, 33, v64
	global_load_dwordx2 v[178:179], v65, s[70:71]
	global_load_dwordx2 v[176:177], v65, s[70:71] offset:128
	global_load_dwordx2 v[172:173], v70, s[70:71]
	global_load_dwordx2 v[170:171], v70, s[70:71] offset:128
	v_lshlrev_b32_e32 v65, 5, v162
	v_lshlrev_b32_e32 v70, 5, v156
	v_and_or_b32 v65, v65, s44, v108
	v_and_or_b32 v70, v70, s41, v108
	v_lshlrev_b32_e32 v65, 3, v65
	v_lshlrev_b32_e32 v70, 3, v70
	v_or_b32_e32 v150, 34, v64
	v_or_b32_e32 v144, 35, v64
	global_load_dwordx2 v[166:167], v65, s[70:71]
	global_load_dwordx2 v[164:165], v65, s[70:71] offset:128
	global_load_dwordx2 v[160:161], v70, s[70:71]
	global_load_dwordx2 v[158:159], v70, s[70:71] offset:128
	v_lshlrev_b32_e32 v65, 5, v150
	v_lshlrev_b32_e32 v70, 5, v144
	v_and_or_b32 v65, v65, s42, v108
	v_and_or_b32 v70, v70, s43, v108
	v_lshlrev_b32_e32 v65, 3, v65
	v_lshlrev_b32_e32 v70, 3, v70
	s_waitcnt vmcnt(20)
	v_or_b32_e32 v94, 48, v64
	v_or_b32_e32 v88, 49, v64
	global_load_dwordx2 v[154:155], v65, s[70:71]
	global_load_dwordx2 v[152:153], v65, s[70:71] offset:128
	global_load_dwordx2 v[148:149], v70, s[70:71]
	global_load_dwordx2 v[146:147], v70, s[70:71] offset:128
	v_lshlrev_b32_e32 v65, 5, v94
	v_lshlrev_b32_e32 v70, 5, v88
	v_and_or_b32 v65, v65, s44, v108
	v_and_or_b32 v70, v70, s41, v108
	v_lshlrev_b32_e32 v65, 3, v65
	v_lshlrev_b32_e32 v70, 3, v70
	v_or_b32_e32 v78, 50, v64
	global_load_dwordx2 v[142:143], v65, s[70:71]
	global_load_dwordx2 v[140:141], v65, s[70:71] offset:128
	global_load_dwordx2 v[92:93], v70, s[70:71]
	global_load_dwordx2 v[90:91], v70, s[70:71] offset:128
	v_lshlrev_b32_e32 v65, 5, v78
	v_or_b32_e32 v70, 51, v64
	v_and_or_b32 v65, v65, s42, v108
	v_lshlrev_b32_e32 v71, 5, v70
	v_lshlrev_b32_e32 v65, 3, v65
	v_and_or_b32 v71, v71, s43, v108
	v_lshlrev_b32_e32 v71, 3, v71
	global_load_dwordx2 v[82:83], v65, s[70:71]
	global_load_dwordx2 v[80:81], v65, s[70:71] offset:128
	global_load_dwordx2 v[74:75], v71, s[70:71]
	global_load_dwordx2 v[72:73], v71, s[70:71] offset:128
	s_and_b64 vcc, exec, s[4:5]
	v_readlane_b32 s57, v250, 25
	v_readlane_b32 s58, v250, 26
	v_readlane_b32 s59, v250, 27
	v_readlane_b32 s60, v250, 28
	v_readlane_b32 s61, v250, 29
	v_readlane_b32 s62, v250, 30
	v_readlane_b32 s63, v250, 31
	v_readlane_b32 s64, v250, 32
	v_readlane_b32 s65, v250, 33
	v_readlane_b32 s66, v250, 34
	v_readlane_b32 s67, v250, 35
	v_readlane_b32 s68, v250, 36
	v_readlane_b32 s69, v250, 37
	s_cbranch_vccnz .LBB0_334
	v_mov_b32_e32 v76, v44
	v_mov_b32_e32 v77, v52
	v_and_b32_e32 v79, 64, v121
	v_pk_mul_f32 v[210:211], v[76:77], v[76:77]
	v_mov_b32_e32 v212, v56
	v_mov_b32_e32 v213, v60
	v_add_u32_e32 v79, 64, v79
	v_pk_mul_f32 v[212:213], v[212:213], v[212:213]
	v_add_f32_e32 v65, v210, v211
	v_add_f32_e32 v65, v213, v65
	v_add_f32_e32 v65, v212, v65
	s_nop 1
	v_add_f32_dpp v65, v65, v65 quad_perm:[1,0,3,2] row_mask:0xf bank_mask:0xf
	s_waitcnt lgkmcnt(0)
	s_nop 1
	s_nop 1
	v_add_f32_dpp v65, v65, v65 quad_perm:[2,3,0,1] row_mask:0xf bank_mask:0xf
	s_waitcnt lgkmcnt(0)
	s_nop 1
	s_nop 1
	v_add_f32_dpp v65, v65, v65 row_half_mirror row_mask:0xf bank_mask:0xf
	s_waitcnt lgkmcnt(0)
	s_nop 1
	s_nop 1
	v_add_f32_dpp v65, v65, v65 row_mirror row_mask:0xf bank_mask:0xf
	s_waitcnt lgkmcnt(0)
	v_fmamk_f32 v65, v65, 0x3c800000, v113
	v_mul_f32_e32 v71, 0x4b800000, v65
	v_cmp_gt_f32_e32 vcc, s45, v65
	s_nop 1
	v_cndmask_b32_e32 v65, v65, v71, vcc
	v_rsq_f32_e32 v65, v65
	s_nop 0
	v_mul_f32_e32 v71, 0x45800000, v65
	v_cndmask_b32_e32 v100, v65, v71, vcc
	v_pk_mul_f32 v[76:77], v[76:77], v[100:101] op_sel_hi:[1,0]
	s_nop 0
	v_pk_mul_f32 v[210:211], v[66:67], v[76:77]
	v_mov_b32_e32 v76, v60
	v_mov_b32_e32 v77, v56
	v_pk_mul_f32 v[76:77], v[76:77], v[100:101] op_sel_hi:[1,0]
	s_nop 0
	v_pk_mul_f32 v[212:213], v[68:69], v[76:77]
	s_branch .LBB0_335

.LBB0_338:
	v_mov_b32_e32 v100, v61
	v_and_b32_e32 v79, 64, v121
	v_pk_mul_f32 v[210:211], v[208:209], v[208:209]
	v_pk_mov_b32 v[212:213], v[56:57], v[100:101] op_sel:[1,0]
	v_add_u32_e32 v79, 64, v79
	v_pk_mul_f32 v[212:213], v[212:213], v[212:213]
	v_add_f32_e32 v65, v210, v211
	v_add_f32_e32 v65, v213, v65
	v_add_f32_e32 v65, v212, v65
	s_nop 1
	v_add_f32_dpp v65, v65, v65 quad_perm:[1,0,3,2] row_mask:0xf bank_mask:0xf
	v_mov_b32_e32 v210, v61
	v_mov_b32_e32 v211, v57
	s_waitcnt lgkmcnt(0)
	s_nop 1
	s_nop 1
	v_add_f32_dpp v65, v65, v65 quad_perm:[2,3,0,1] row_mask:0xf bank_mask:0xf
	s_waitcnt lgkmcnt(0)
	s_nop 1
	s_nop 1
	v_add_f32_dpp v65, v65, v65 row_half_mirror row_mask:0xf bank_mask:0xf
	s_waitcnt lgkmcnt(0)
	s_nop 1
	s_nop 1
	v_add_f32_dpp v65, v65, v65 row_mirror row_mask:0xf bank_mask:0xf
	s_waitcnt lgkmcnt(0)
	v_fmamk_f32 v65, v65, 0x3c800000, v113
	v_mul_f32_e32 v71, 0x4b800000, v65
	v_cmp_gt_f32_e32 vcc, s45, v65
	s_nop 1
	v_cndmask_b32_e32 v65, v65, v71, vcc
	v_rsq_f32_e32 v65, v65
	s_nop 0
	v_mul_f32_e32 v71, 0x45800000, v65
	v_cndmask_b32_e32 v100, v65, v71, vcc
	v_pk_mul_f32 v[208:209], v[208:209], v[100:101] op_sel_hi:[1,0]
	v_pk_mul_f32 v[210:211], v[210:211], v[100:101] op_sel_hi:[1,0]
	v_pk_mul_f32 v[208:209], v[66:67], v[208:209]
	v_pk_mul_f32 v[210:211], v[68:69], v[210:211]
	s_branch .LBB0_342

.LBB0_345:
	v_and_b32_e32 v79, 64, v121
	v_pk_mul_f32 v[208:209], v[206:207], v[206:207]
	v_mov_b32_e32 v210, v58
	v_mov_b32_e32 v211, v62
	v_add_u32_e32 v79, 64, v79
	v_pk_mul_f32 v[210:211], v[210:211], v[210:211]
	v_add_f32_e32 v65, v208, v209
	v_add_f32_e32 v65, v211, v65
	v_add_f32_e32 v65, v210, v65
	s_nop 1
	v_add_f32_dpp v65, v65, v65 quad_perm:[1,0,3,2] row_mask:0xf bank_mask:0xf
	v_mov_b32_e32 v208, v62
	v_mov_b32_e32 v209, v58
	s_waitcnt lgkmcnt(0)
	s_nop 1
	s_nop 1
	v_add_f32_dpp v65, v65, v65 quad_perm:[2,3,0,1] row_mask:0xf bank_mask:0xf
	s_waitcnt lgkmcnt(0)
	s_nop 1
	s_nop 1
	v_add_f32_dpp v65, v65, v65 row_half_mirror row_mask:0xf bank_mask:0xf
	s_waitcnt lgkmcnt(0)
	s_nop 1
	s_nop 1
	v_add_f32_dpp v65, v65, v65 row_mirror row_mask:0xf bank_mask:0xf
	s_waitcnt lgkmcnt(0)
	v_fmamk_f32 v65, v65, 0x3c800000, v113
	v_mul_f32_e32 v71, 0x4b800000, v65
	v_cmp_gt_f32_e32 vcc, s45, v65
	s_nop 1
	v_cndmask_b32_e32 v65, v65, v71, vcc
	v_rsq_f32_e32 v65, v65
	s_nop 0
	v_mul_f32_e32 v71, 0x45800000, v65
	v_cndmask_b32_e32 v100, v65, v71, vcc
	v_pk_mul_f32 v[206:207], v[206:207], v[100:101] op_sel_hi:[1,0]
	v_pk_mul_f32 v[208:209], v[208:209], v[100:101] op_sel_hi:[1,0]
	v_pk_mul_f32 v[206:207], v[66:67], v[206:207]
	v_pk_mul_f32 v[208:209], v[68:69], v[208:209]
	s_branch .LBB0_349

.LBB0_352:
	v_mov_b32_e32 v100, v63
	v_and_b32_e32 v79, 64, v121
	v_pk_mul_f32 v[200:201], v[198:199], v[198:199]
	v_pk_mov_b32 v[202:203], v[58:59], v[100:101] op_sel:[1,0]
	v_add_u32_e32 v79, 64, v79
	v_pk_mul_f32 v[202:203], v[202:203], v[202:203]
	v_add_f32_e32 v65, v200, v201
	v_add_f32_e32 v65, v203, v65
	v_add_f32_e32 v65, v202, v65
	s_nop 1
	v_add_f32_dpp v65, v65, v65 quad_perm:[1,0,3,2] row_mask:0xf bank_mask:0xf
	v_mov_b32_e32 v200, v63
	v_mov_b32_e32 v201, v59
	s_waitcnt lgkmcnt(0)
	s_nop 1
	s_nop 1
	v_add_f32_dpp v65, v65, v65 quad_perm:[2,3,0,1] row_mask:0xf bank_mask:0xf
	s_waitcnt lgkmcnt(0)
	s_nop 1
	s_nop 1
	v_add_f32_dpp v65, v65, v65 row_half_mirror row_mask:0xf bank_mask:0xf
	s_waitcnt lgkmcnt(0)
	s_nop 1
	s_nop 1
	v_add_f32_dpp v65, v65, v65 row_mirror row_mask:0xf bank_mask:0xf
	s_waitcnt lgkmcnt(0)
	v_fmamk_f32 v65, v65, 0x3c800000, v113
	v_mul_f32_e32 v71, 0x4b800000, v65
	v_cmp_gt_f32_e32 vcc, s45, v65
	s_nop 1
	v_cndmask_b32_e32 v65, v65, v71, vcc
	v_rsq_f32_e32 v65, v65
	s_nop 0
	v_mul_f32_e32 v71, 0x45800000, v65
	v_cndmask_b32_e32 v100, v65, v71, vcc
	v_pk_mul_f32 v[198:199], v[198:199], v[100:101] op_sel_hi:[1,0]
	v_pk_mul_f32 v[200:201], v[200:201], v[100:101] op_sel_hi:[1,0]
	v_pk_mul_f32 v[198:199], v[66:67], v[198:199]
	v_pk_mul_f32 v[200:201], v[68:69], v[200:201]
	s_branch .LBB0_356

.LBB0_359:
	v_and_b32_e32 v79, 64, v121
	v_pk_mul_f32 v[194:195], v[192:193], v[192:193]
	v_mov_b32_e32 v196, v28
	v_mov_b32_e32 v197, v32
	v_add_u32_e32 v79, 64, v79
	v_pk_mul_f32 v[196:197], v[196:197], v[196:197]
	v_add_f32_e32 v65, v194, v195
	v_add_f32_e32 v65, v197, v65
	v_add_f32_e32 v65, v196, v65
	s_nop 1
	v_add_f32_dpp v65, v65, v65 quad_perm:[1,0,3,2] row_mask:0xf bank_mask:0xf
	v_mov_b32_e32 v194, v32
	v_mov_b32_e32 v195, v28
	s_waitcnt lgkmcnt(0)
	s_nop 1
	s_nop 1
	v_add_f32_dpp v65, v65, v65 quad_perm:[2,3,0,1] row_mask:0xf bank_mask:0xf
	s_waitcnt lgkmcnt(0)
	s_nop 1
	s_nop 1
	v_add_f32_dpp v65, v65, v65 row_half_mirror row_mask:0xf bank_mask:0xf
	s_waitcnt lgkmcnt(0)
	s_nop 1
	s_nop 1
	v_add_f32_dpp v65, v65, v65 row_mirror row_mask:0xf bank_mask:0xf
	s_waitcnt lgkmcnt(0)
	v_fmamk_f32 v65, v65, 0x3c800000, v113
	v_mul_f32_e32 v71, 0x4b800000, v65
	v_cmp_gt_f32_e32 vcc, s45, v65
	s_nop 1
	v_cndmask_b32_e32 v65, v65, v71, vcc
	v_rsq_f32_e32 v65, v65
	s_nop 0
	v_mul_f32_e32 v71, 0x45800000, v65
	v_cndmask_b32_e32 v100, v65, v71, vcc
	v_pk_mul_f32 v[192:193], v[192:193], v[100:101] op_sel_hi:[1,0]
	v_pk_mul_f32 v[194:195], v[194:195], v[100:101] op_sel_hi:[1,0]
	v_pk_mul_f32 v[192:193], v[66:67], v[192:193]
	v_pk_mul_f32 v[194:195], v[68:69], v[194:195]
	s_branch .LBB0_363

.LBB0_366:
	v_mov_b32_e32 v100, v33
	v_and_b32_e32 v79, 64, v121
	v_pk_mul_f32 v[188:189], v[186:187], v[186:187]
	v_pk_mov_b32 v[190:191], v[28:29], v[100:101] op_sel:[1,0]
	v_add_u32_e32 v79, 64, v79
	v_pk_mul_f32 v[190:191], v[190:191], v[190:191]
	v_add_f32_e32 v65, v188, v189
	v_add_f32_e32 v65, v191, v65
	v_add_f32_e32 v65, v190, v65
	s_nop 1
	v_add_f32_dpp v65, v65, v65 quad_perm:[1,0,3,2] row_mask:0xf bank_mask:0xf
	v_mov_b32_e32 v188, v33
	v_mov_b32_e32 v189, v29
	s_waitcnt lgkmcnt(0)
	s_nop 1
	s_nop 1
	v_add_f32_dpp v65, v65, v65 quad_perm:[2,3,0,1] row_mask:0xf bank_mask:0xf
	s_waitcnt lgkmcnt(0)
	s_nop 1
	s_nop 1
	v_add_f32_dpp v65, v65, v65 row_half_mirror row_mask:0xf bank_mask:0xf
	s_waitcnt lgkmcnt(0)
	s_nop 1
	s_nop 1
	v_add_f32_dpp v65, v65, v65 row_mirror row_mask:0xf bank_mask:0xf
	s_waitcnt lgkmcnt(0)
	v_fmamk_f32 v65, v65, 0x3c800000, v113
	v_mul_f32_e32 v71, 0x4b800000, v65
	v_cmp_gt_f32_e32 vcc, s45, v65
	s_nop 1
	v_cndmask_b32_e32 v65, v65, v71, vcc
	v_rsq_f32_e32 v65, v65
	s_nop 0
	v_mul_f32_e32 v71, 0x45800000, v65
	v_cndmask_b32_e32 v100, v65, v71, vcc
	v_pk_mul_f32 v[186:187], v[186:187], v[100:101] op_sel_hi:[1,0]
	v_pk_mul_f32 v[188:189], v[188:189], v[100:101] op_sel_hi:[1,0]
	v_pk_mul_f32 v[186:187], v[66:67], v[186:187]
	v_pk_mul_f32 v[188:189], v[68:69], v[188:189]
	s_branch .LBB0_370

.LBB0_373:
	v_and_b32_e32 v79, 64, v121
	v_pk_mul_f32 v[182:183], v[180:181], v[180:181]
	v_mov_b32_e32 v184, v30
	v_mov_b32_e32 v185, v34
	v_add_u32_e32 v79, 64, v79
	v_pk_mul_f32 v[184:185], v[184:185], v[184:185]
	v_add_f32_e32 v65, v182, v183
	v_add_f32_e32 v65, v185, v65
	v_add_f32_e32 v65, v184, v65
	s_nop 1
	v_add_f32_dpp v65, v65, v65 quad_perm:[1,0,3,2] row_mask:0xf bank_mask:0xf
	v_mov_b32_e32 v182, v34
	v_mov_b32_e32 v183, v30
	s_waitcnt lgkmcnt(0)
	s_nop 1
	s_nop 1
	v_add_f32_dpp v65, v65, v65 quad_perm:[2,3,0,1] row_mask:0xf bank_mask:0xf
	s_waitcnt lgkmcnt(0)
	s_nop 1
	s_nop 1
	v_add_f32_dpp v65, v65, v65 row_half_mirror row_mask:0xf bank_mask:0xf
	s_waitcnt lgkmcnt(0)
	s_nop 1
	s_nop 1
	v_add_f32_dpp v65, v65, v65 row_mirror row_mask:0xf bank_mask:0xf
	s_waitcnt lgkmcnt(0)
	v_fmamk_f32 v65, v65, 0x3c800000, v113
	v_mul_f32_e32 v71, 0x4b800000, v65
	v_cmp_gt_f32_e32 vcc, s45, v65
	s_nop 1
	v_cndmask_b32_e32 v65, v65, v71, vcc
	v_rsq_f32_e32 v65, v65
	s_nop 0
	v_mul_f32_e32 v71, 0x45800000, v65
	v_cndmask_b32_e32 v100, v65, v71, vcc
	v_pk_mul_f32 v[180:181], v[180:181], v[100:101] op_sel_hi:[1,0]
	v_pk_mul_f32 v[182:183], v[182:183], v[100:101] op_sel_hi:[1,0]
	v_pk_mul_f32 v[180:181], v[66:67], v[180:181]
	v_pk_mul_f32 v[182:183], v[68:69], v[182:183]
	s_branch .LBB0_377

.LBB0_380:
	v_mov_b32_e32 v100, v35
	v_and_b32_e32 v79, 64, v121
	v_pk_mul_f32 v[176:177], v[174:175], v[174:175]
	v_pk_mov_b32 v[178:179], v[30:31], v[100:101] op_sel:[1,0]
	v_add_u32_e32 v79, 64, v79
	v_pk_mul_f32 v[178:179], v[178:179], v[178:179]
	v_add_f32_e32 v65, v176, v177
	v_add_f32_e32 v65, v179, v65
	v_add_f32_e32 v65, v178, v65
	s_nop 1
	v_add_f32_dpp v65, v65, v65 quad_perm:[1,0,3,2] row_mask:0xf bank_mask:0xf
	v_mov_b32_e32 v176, v35
	v_mov_b32_e32 v177, v31
	s_waitcnt lgkmcnt(0)
	s_nop 1
	s_nop 1
	v_add_f32_dpp v65, v65, v65 quad_perm:[2,3,0,1] row_mask:0xf bank_mask:0xf
	s_waitcnt lgkmcnt(0)
	s_nop 1
	s_nop 1
	v_add_f32_dpp v65, v65, v65 row_half_mirror row_mask:0xf bank_mask:0xf
	s_waitcnt lgkmcnt(0)
	s_nop 1
	s_nop 1
	v_add_f32_dpp v65, v65, v65 row_mirror row_mask:0xf bank_mask:0xf
	s_waitcnt lgkmcnt(0)
	v_fmamk_f32 v65, v65, 0x3c800000, v113
	v_mul_f32_e32 v71, 0x4b800000, v65
	v_cmp_gt_f32_e32 vcc, s45, v65
	s_nop 1
	v_cndmask_b32_e32 v65, v65, v71, vcc
	v_rsq_f32_e32 v65, v65
	s_nop 0
	v_mul_f32_e32 v71, 0x45800000, v65
	v_cndmask_b32_e32 v100, v65, v71, vcc
	v_pk_mul_f32 v[174:175], v[174:175], v[100:101] op_sel_hi:[1,0]
	v_pk_mul_f32 v[176:177], v[176:177], v[100:101] op_sel_hi:[1,0]
	v_pk_mul_f32 v[174:175], v[66:67], v[174:175]
	v_pk_mul_f32 v[176:177], v[68:69], v[176:177]
	s_branch .LBB0_384

.LBB0_387:
	v_and_b32_e32 v79, 64, v121
	v_pk_mul_f32 v[170:171], v[168:169], v[168:169]
	v_mov_b32_e32 v172, v12
	v_mov_b32_e32 v173, v16
	v_add_u32_e32 v79, 64, v79
	v_pk_mul_f32 v[172:173], v[172:173], v[172:173]
	v_add_f32_e32 v65, v170, v171
	v_add_f32_e32 v65, v173, v65
	v_add_f32_e32 v65, v172, v65
	s_nop 1
	v_add_f32_dpp v65, v65, v65 quad_perm:[1,0,3,2] row_mask:0xf bank_mask:0xf
	v_mov_b32_e32 v170, v16
	v_mov_b32_e32 v171, v12
	s_waitcnt lgkmcnt(0)
	s_nop 1
	s_nop 1
	v_add_f32_dpp v65, v65, v65 quad_perm:[2,3,0,1] row_mask:0xf bank_mask:0xf
	s_waitcnt lgkmcnt(0)
	s_nop 1
	s_nop 1
	v_add_f32_dpp v65, v65, v65 row_half_mirror row_mask:0xf bank_mask:0xf
	s_waitcnt lgkmcnt(0)
	s_nop 1
	s_nop 1
	v_add_f32_dpp v65, v65, v65 row_mirror row_mask:0xf bank_mask:0xf
	s_waitcnt lgkmcnt(0)
	v_fmamk_f32 v65, v65, 0x3c800000, v113
	v_mul_f32_e32 v71, 0x4b800000, v65
	v_cmp_gt_f32_e32 vcc, s45, v65
	s_nop 1
	v_cndmask_b32_e32 v65, v65, v71, vcc
	v_rsq_f32_e32 v65, v65
	s_nop 0
	v_mul_f32_e32 v71, 0x45800000, v65
	v_cndmask_b32_e32 v100, v65, v71, vcc
	v_pk_mul_f32 v[168:169], v[168:169], v[100:101] op_sel_hi:[1,0]
	v_pk_mul_f32 v[170:171], v[170:171], v[100:101] op_sel_hi:[1,0]
	v_pk_mul_f32 v[168:169], v[66:67], v[168:169]
	v_pk_mul_f32 v[170:171], v[68:69], v[170:171]
	s_branch .LBB0_391

.LBB0_394:
	v_mov_b32_e32 v100, v17
	v_and_b32_e32 v79, 64, v121
	v_pk_mul_f32 v[164:165], v[162:163], v[162:163]
	v_pk_mov_b32 v[166:167], v[12:13], v[100:101] op_sel:[1,0]
	v_add_u32_e32 v79, 64, v79
	v_pk_mul_f32 v[166:167], v[166:167], v[166:167]
	v_add_f32_e32 v65, v164, v165
	v_add_f32_e32 v65, v167, v65
	v_add_f32_e32 v65, v166, v65
	s_nop 1
	v_add_f32_dpp v65, v65, v65 quad_perm:[1,0,3,2] row_mask:0xf bank_mask:0xf
	v_mov_b32_e32 v164, v17
	v_mov_b32_e32 v165, v13
	s_waitcnt lgkmcnt(0)
	s_nop 1
	s_nop 1
	v_add_f32_dpp v65, v65, v65 quad_perm:[2,3,0,1] row_mask:0xf bank_mask:0xf
	s_waitcnt lgkmcnt(0)
	s_nop 1
	s_nop 1
	v_add_f32_dpp v65, v65, v65 row_half_mirror row_mask:0xf bank_mask:0xf
	s_waitcnt lgkmcnt(0)
	s_nop 1
	s_nop 1
	v_add_f32_dpp v65, v65, v65 row_mirror row_mask:0xf bank_mask:0xf
	s_waitcnt lgkmcnt(0)
	v_fmamk_f32 v65, v65, 0x3c800000, v113
	v_mul_f32_e32 v71, 0x4b800000, v65
	v_cmp_gt_f32_e32 vcc, s45, v65
	s_nop 1
	v_cndmask_b32_e32 v65, v65, v71, vcc
	v_rsq_f32_e32 v65, v65
	s_nop 0
	v_mul_f32_e32 v71, 0x45800000, v65
	v_cndmask_b32_e32 v100, v65, v71, vcc
	v_pk_mul_f32 v[162:163], v[162:163], v[100:101] op_sel_hi:[1,0]
	v_pk_mul_f32 v[164:165], v[164:165], v[100:101] op_sel_hi:[1,0]
	v_pk_mul_f32 v[162:163], v[66:67], v[162:163]
	v_pk_mul_f32 v[164:165], v[68:69], v[164:165]
	s_branch .LBB0_398

.LBB0_401:
	v_and_b32_e32 v79, 64, v121
	v_pk_mul_f32 v[158:159], v[156:157], v[156:157]
	v_mov_b32_e32 v160, v14
	v_mov_b32_e32 v161, v18
	v_add_u32_e32 v79, 64, v79
	v_pk_mul_f32 v[160:161], v[160:161], v[160:161]
	v_add_f32_e32 v65, v158, v159
	v_add_f32_e32 v65, v161, v65
	v_add_f32_e32 v65, v160, v65
	s_nop 1
	v_add_f32_dpp v65, v65, v65 quad_perm:[1,0,3,2] row_mask:0xf bank_mask:0xf
	v_mov_b32_e32 v158, v18
	v_mov_b32_e32 v159, v14
	s_waitcnt lgkmcnt(0)
	s_nop 1
	s_nop 1
	v_add_f32_dpp v65, v65, v65 quad_perm:[2,3,0,1] row_mask:0xf bank_mask:0xf
	s_waitcnt lgkmcnt(0)
	s_nop 1
	s_nop 1
	v_add_f32_dpp v65, v65, v65 row_half_mirror row_mask:0xf bank_mask:0xf
	s_waitcnt lgkmcnt(0)
	s_nop 1
	s_nop 1
	v_add_f32_dpp v65, v65, v65 row_mirror row_mask:0xf bank_mask:0xf
	s_waitcnt lgkmcnt(0)
	v_fmamk_f32 v65, v65, 0x3c800000, v113
	v_mul_f32_e32 v71, 0x4b800000, v65
	v_cmp_gt_f32_e32 vcc, s45, v65
	s_nop 1
	v_cndmask_b32_e32 v65, v65, v71, vcc
	v_rsq_f32_e32 v65, v65
	s_nop 0
	v_mul_f32_e32 v71, 0x45800000, v65
	v_cndmask_b32_e32 v100, v65, v71, vcc
	v_pk_mul_f32 v[156:157], v[156:157], v[100:101] op_sel_hi:[1,0]
	v_pk_mul_f32 v[158:159], v[158:159], v[100:101] op_sel_hi:[1,0]
	v_pk_mul_f32 v[156:157], v[66:67], v[156:157]
	v_pk_mul_f32 v[158:159], v[68:69], v[158:159]
	s_branch .LBB0_405

.LBB0_408:
	v_mov_b32_e32 v100, v19
	v_and_b32_e32 v79, 64, v121
	v_pk_mul_f32 v[152:153], v[150:151], v[150:151]
	v_pk_mov_b32 v[154:155], v[14:15], v[100:101] op_sel:[1,0]
	v_add_u32_e32 v79, 64, v79
	v_pk_mul_f32 v[154:155], v[154:155], v[154:155]
	v_add_f32_e32 v65, v152, v153
	v_add_f32_e32 v65, v155, v65
	v_add_f32_e32 v65, v154, v65
	s_nop 1
	v_add_f32_dpp v65, v65, v65 quad_perm:[1,0,3,2] row_mask:0xf bank_mask:0xf
	v_mov_b32_e32 v152, v19
	v_mov_b32_e32 v153, v15
	s_waitcnt lgkmcnt(0)
	s_nop 1
	s_nop 1
	v_add_f32_dpp v65, v65, v65 quad_perm:[2,3,0,1] row_mask:0xf bank_mask:0xf
	s_waitcnt lgkmcnt(0)
	s_nop 1
	s_nop 1
	v_add_f32_dpp v65, v65, v65 row_half_mirror row_mask:0xf bank_mask:0xf
	s_waitcnt lgkmcnt(0)
	s_nop 1
	s_nop 1
	v_add_f32_dpp v65, v65, v65 row_mirror row_mask:0xf bank_mask:0xf
	s_waitcnt lgkmcnt(0)
	v_fmamk_f32 v65, v65, 0x3c800000, v113
	v_mul_f32_e32 v71, 0x4b800000, v65
	v_cmp_gt_f32_e32 vcc, s45, v65
	s_nop 1
	v_cndmask_b32_e32 v65, v65, v71, vcc
	v_rsq_f32_e32 v65, v65
	s_nop 0
	v_mul_f32_e32 v71, 0x45800000, v65
	v_cndmask_b32_e32 v100, v65, v71, vcc
	v_pk_mul_f32 v[150:151], v[150:151], v[100:101] op_sel_hi:[1,0]
	v_pk_mul_f32 v[152:153], v[152:153], v[100:101] op_sel_hi:[1,0]
	v_pk_mul_f32 v[150:151], v[66:67], v[150:151]
	v_pk_mul_f32 v[152:153], v[68:69], v[152:153]
	s_branch .LBB0_412

.LBB0_415:
	v_and_b32_e32 v79, 64, v121
	v_pk_mul_f32 v[146:147], v[144:145], v[144:145]
	v_mov_b32_e32 v148, v48
	v_mov_b32_e32 v149, v0
	v_add_u32_e32 v79, 64, v79
	v_pk_mul_f32 v[148:149], v[148:149], v[148:149]
	v_add_f32_e32 v65, v146, v147
	v_add_f32_e32 v65, v149, v65
	v_add_f32_e32 v65, v148, v65
	s_nop 1
	v_add_f32_dpp v65, v65, v65 quad_perm:[1,0,3,2] row_mask:0xf bank_mask:0xf
	v_mov_b32_e32 v146, v0
	v_mov_b32_e32 v147, v48
	s_waitcnt lgkmcnt(0)
	s_nop 1
	s_nop 1
	v_add_f32_dpp v65, v65, v65 quad_perm:[2,3,0,1] row_mask:0xf bank_mask:0xf
	s_waitcnt lgkmcnt(0)
	s_nop 1
	s_nop 1
	v_add_f32_dpp v65, v65, v65 row_half_mirror row_mask:0xf bank_mask:0xf
	s_waitcnt lgkmcnt(0)
	s_nop 1
	s_nop 1
	v_add_f32_dpp v65, v65, v65 row_mirror row_mask:0xf bank_mask:0xf
	s_waitcnt lgkmcnt(0)
	v_fmamk_f32 v65, v65, 0x3c800000, v113
	v_mul_f32_e32 v71, 0x4b800000, v65
	v_cmp_gt_f32_e32 vcc, s45, v65
	s_nop 1
	v_cndmask_b32_e32 v65, v65, v71, vcc
	v_rsq_f32_e32 v65, v65
	s_nop 0
	v_mul_f32_e32 v71, 0x45800000, v65
	v_cndmask_b32_e32 v100, v65, v71, vcc
	v_pk_mul_f32 v[144:145], v[144:145], v[100:101] op_sel_hi:[1,0]
	v_pk_mul_f32 v[146:147], v[146:147], v[100:101] op_sel_hi:[1,0]
	v_pk_mul_f32 v[144:145], v[66:67], v[144:145]
	v_pk_mul_f32 v[146:147], v[68:69], v[146:147]
	s_branch .LBB0_419

.LBB0_422:
	v_mov_b32_e32 v100, v1
	v_and_b32_e32 v79, 64, v121
	v_pk_mul_f32 v[140:141], v[94:95], v[94:95]
	v_pk_mov_b32 v[142:143], v[48:49], v[100:101] op_sel:[1,0]
	v_add_u32_e32 v79, 64, v79
	v_pk_mul_f32 v[142:143], v[142:143], v[142:143]
	v_add_f32_e32 v65, v140, v141
	v_add_f32_e32 v65, v143, v65
	v_add_f32_e32 v65, v142, v65
	s_nop 1
	v_add_f32_dpp v65, v65, v65 quad_perm:[1,0,3,2] row_mask:0xf bank_mask:0xf
	v_mov_b32_e32 v140, v1
	v_mov_b32_e32 v141, v49
	s_waitcnt lgkmcnt(0)
	s_nop 1
	s_nop 1
	v_add_f32_dpp v65, v65, v65 quad_perm:[2,3,0,1] row_mask:0xf bank_mask:0xf
	s_waitcnt lgkmcnt(0)
	s_nop 1
	s_nop 1
	v_add_f32_dpp v65, v65, v65 row_half_mirror row_mask:0xf bank_mask:0xf
	s_waitcnt lgkmcnt(0)
	s_nop 1
	s_nop 1
	v_add_f32_dpp v65, v65, v65 row_mirror row_mask:0xf bank_mask:0xf
	s_waitcnt lgkmcnt(0)
	v_fmamk_f32 v65, v65, 0x3c800000, v113
	v_mul_f32_e32 v71, 0x4b800000, v65
	v_cmp_gt_f32_e32 vcc, s45, v65
	s_nop 1
	v_cndmask_b32_e32 v65, v65, v71, vcc
	v_rsq_f32_e32 v65, v65
	s_nop 0
	v_mul_f32_e32 v71, 0x45800000, v65
	v_cndmask_b32_e32 v100, v65, v71, vcc
	v_pk_mul_f32 v[94:95], v[94:95], v[100:101] op_sel_hi:[1,0]
	v_pk_mul_f32 v[140:141], v[140:141], v[100:101] op_sel_hi:[1,0]
	v_pk_mul_f32 v[94:95], v[66:67], v[94:95]
	v_pk_mul_f32 v[140:141], v[68:69], v[140:141]
	s_branch .LBB0_426

.LBB0_429:
	v_and_b32_e32 v79, 64, v121
	v_pk_mul_f32 v[90:91], v[88:89], v[88:89]
	v_mov_b32_e32 v92, v50
	v_mov_b32_e32 v93, v2
	v_add_u32_e32 v79, 64, v79
	v_pk_mul_f32 v[92:93], v[92:93], v[92:93]
	v_add_f32_e32 v65, v90, v91
	v_add_f32_e32 v65, v93, v65
	v_add_f32_e32 v65, v92, v65
	s_nop 1
	v_add_f32_dpp v65, v65, v65 quad_perm:[1,0,3,2] row_mask:0xf bank_mask:0xf
	v_mov_b32_e32 v92, v2
	v_mov_b32_e32 v93, v50
	s_waitcnt lgkmcnt(0)
	s_nop 1
	s_nop 1
	v_add_f32_dpp v65, v65, v65 quad_perm:[2,3,0,1] row_mask:0xf bank_mask:0xf
	s_waitcnt lgkmcnt(0)
	s_nop 1
	s_nop 1
	v_add_f32_dpp v65, v65, v65 row_half_mirror row_mask:0xf bank_mask:0xf
	s_waitcnt lgkmcnt(0)
	s_nop 1
	s_nop 1
	v_add_f32_dpp v65, v65, v65 row_mirror row_mask:0xf bank_mask:0xf
	s_waitcnt lgkmcnt(0)
	v_fmamk_f32 v65, v65, 0x3c800000, v113
	v_mul_f32_e32 v71, 0x4b800000, v65
	v_cmp_gt_f32_e32 vcc, s45, v65
	s_nop 1
	v_cndmask_b32_e32 v65, v65, v71, vcc
	v_rsq_f32_e32 v65, v65
	s_nop 0
	v_mul_f32_e32 v71, 0x45800000, v65
	v_cndmask_b32_e32 v90, v65, v71, vcc
	v_pk_mul_f32 v[88:89], v[88:89], v[90:91] op_sel_hi:[1,0]
	v_pk_mul_f32 v[90:91], v[92:93], v[90:91] op_sel_hi:[1,0]
	v_pk_mul_f32 v[88:89], v[66:67], v[88:89]
	v_pk_mul_f32 v[90:91], v[68:69], v[90:91]
	s_branch .LBB0_433

.LBB0_436:
	v_mov_b32_e32 v78, v11
	v_mov_b32_e32 v79, v7
	v_pk_mul_f32 v[80:81], v[78:79], v[78:79]
	v_mov_b32_e32 v82, v3
	v_add_f32_e32 v65, v80, v81
	v_and_b32_e32 v80, 64, v121
	v_pk_mov_b32 v[82:83], v[50:51], v[82:83] op_sel:[1,0]
	v_add_u32_e32 v80, 64, v80
	v_pk_mul_f32 v[82:83], v[82:83], v[82:83]
	v_cmp_lt_i32_e32 vcc, v71, v80
	v_add_f32_e32 v65, v83, v65
	v_add_f32_e32 v65, v82, v65
	s_nop 1
	v_add_f32_dpp v65, v65, v65 quad_perm:[1,0,3,2] row_mask:0xf bank_mask:0xf
	s_waitcnt lgkmcnt(0)
	v_cmp_lt_i32_e32 vcc, v71, v80
	s_nop 1
	s_nop 1
	v_add_f32_dpp v65, v65, v65 quad_perm:[2,3,0,1] row_mask:0xf bank_mask:0xf
	s_waitcnt lgkmcnt(0)
	v_cmp_lt_i32_e32 vcc, v71, v80
	s_nop 1
	s_nop 1
	v_add_f32_dpp v65, v65, v65 row_half_mirror row_mask:0xf bank_mask:0xf
	s_waitcnt lgkmcnt(0)
	v_cmp_lt_i32_e32 vcc, v71, v80
	s_nop 1
	s_nop 1
	v_add_f32_dpp v65, v65, v65 row_mirror row_mask:0xf bank_mask:0xf
	s_waitcnt lgkmcnt(0)
	v_fmamk_f32 v65, v65, 0x3c800000, v113
	v_mul_f32_e32 v71, 0x4b800000, v65
	v_cmp_gt_f32_e32 vcc, s45, v65
	s_nop 1
	v_cndmask_b32_e32 v65, v65, v71, vcc
	v_rsq_f32_e32 v65, v65
	s_nop 0
	v_mul_f32_e32 v71, 0x45800000, v65
	v_cndmask_b32_e32 v80, v65, v71, vcc
	v_pk_mul_f32 v[78:79], v[78:79], v[80:81] op_sel_hi:[1,0]
	s_nop 0
	v_pk_mul_f32 v[66:67], v[66:67], v[78:79]
	v_mov_b32_e32 v78, v3
	v_mov_b32_e32 v79, v51
	v_pk_mul_f32 v[78:79], v[78:79], v[80:81] op_sel_hi:[1,0]
	s_nop 0
	v_pk_mul_f32 v[68:69], v[68:69], v[78:79]
	s_branch .LBB0_440

.LBB0_765:
	s_nop 1
	v_add_u32_dpp v251, v251, v251 quad_perm:[1,0,3,2] row_mask:0xf bank_mask:0xf
	s_nop 1
	v_add_u32_dpp v251, v251, v251 quad_perm:[2,3,0,1] row_mask:0xf bank_mask:0xf
	s_nop 1
	v_add_u32_dpp v251, v251, v251 row_half_mirror row_mask:0xf bank_mask:0xf
	s_nop 1
	v_add_u32_dpp v251, v251, v251 row_mirror row_mask:0xf bank_mask:0xf
	s_nop 1
	v_readlane_b32 s30, v251, 0
	v_readlane_b32 s54, v251, 16
	v_readlane_b32 s55, v251, 32
	v_readlane_b32 s56, v251, 48
	s_add_i32 s30, s30, s54
	s_add_i32 s55, s55, s56
	s_add_i32 s30, s30, s55
	s_cmpk_lg_i32 s30, 0x100
	s_cselect_b64 s[54:55], -1, 0
	s_cmpk_lt_u32 s30, 0x100
	s_cselect_b64 vcc, -1, 0
	v_cndmask_b32_e32 v44, v66, v44, vcc
	v_add_co_u32_e32 v65, vcc, -1, v65
	s_and_b64 s[54:55], s[54:55], vcc
	s_and_b64 vcc, exec, s[54:55]
	s_cbranch_vccz .LBB0_643
.LBB0_766:
	v_lshlrev_b32_e64 v66, v65, 1
	v_or_b32_e32 v66, v66, v44
	v_mov_b32_e32 v251, 0
	v_cmp_ge_u32_e32 vcc, v41, v66
	v_addc_co_u32_e32 v251, vcc, 0, v251, vcc
	v_cmp_ge_u32_e32 vcc, v39, v66
	v_addc_co_u32_e32 v251, vcc, 0, v251, vcc
	v_cmp_ge_u32_e32 vcc, v38, v66
	v_addc_co_u32_e32 v251, vcc, 0, v251, vcc
	v_cmp_ge_u32_e32 vcc, v37, v66
	v_addc_co_u32_e32 v251, vcc, 0, v251, vcc
	v_cmp_ge_u32_e32 vcc, v1, v66
	v_addc_co_u32_e32 v251, vcc, 0, v251, vcc
	v_cmp_ge_u32_e32 vcc, v0, v66
	v_addc_co_u32_e32 v251, vcc, 0, v251, vcc
	v_cmp_ge_u32_e32 vcc, v3, v66
	v_addc_co_u32_e32 v251, vcc, 0, v251, vcc
	v_cmp_ge_u32_e32 vcc, v2, v66
	v_addc_co_u32_e32 v251, vcc, 0, v251, vcc
	s_andn2_b64 vcc, exec, s[36:37]
	s_cbranch_vccnz .LBB0_773
	v_cmp_ge_u32_e32 vcc, v5, v66
	v_addc_co_u32_e32 v251, vcc, 0, v251, vcc
	v_cmp_ge_u32_e32 vcc, v4, v66
	v_addc_co_u32_e32 v251, vcc, 0, v251, vcc
	v_cmp_ge_u32_e32 vcc, v7, v66
	v_addc_co_u32_e32 v251, vcc, 0, v251, vcc
	v_cmp_ge_u32_e32 vcc, v6, v66
	v_addc_co_u32_e32 v251, vcc, 0, v251, vcc
	v_cmp_ge_u32_e32 vcc, v9, v66
	v_addc_co_u32_e32 v251, vcc, 0, v251, vcc
	v_cmp_ge_u32_e32 vcc, v8, v66
	v_addc_co_u32_e32 v251, vcc, 0, v251, vcc
	v_cmp_ge_u32_e32 vcc, v11, v66
	v_addc_co_u32_e32 v251, vcc, 0, v251, vcc
	v_cmp_ge_u32_e32 vcc, v10, v66
	v_addc_co_u32_e32 v251, vcc, 0, v251, vcc
	s_andn2_b64 vcc, exec, s[38:39]
	s_cbranch_vccz .LBB0_774

.LBB0_769:
	v_cmp_ge_u32_e32 vcc, v21, v66
	v_addc_co_u32_e32 v251, vcc, 0, v251, vcc
	v_cmp_ge_u32_e32 vcc, v20, v66
	v_addc_co_u32_e32 v251, vcc, 0, v251, vcc
	v_cmp_ge_u32_e32 vcc, v23, v66
	v_addc_co_u32_e32 v251, vcc, 0, v251, vcc
	v_cmp_ge_u32_e32 vcc, v22, v66
	v_addc_co_u32_e32 v251, vcc, 0, v251, vcc
	v_cmp_ge_u32_e32 vcc, v25, v66
	v_addc_co_u32_e32 v251, vcc, 0, v251, vcc
	v_cmp_ge_u32_e32 vcc, v24, v66
	v_addc_co_u32_e32 v251, vcc, 0, v251, vcc
	v_cmp_ge_u32_e32 vcc, v27, v66
	v_addc_co_u32_e32 v251, vcc, 0, v251, vcc
	v_cmp_ge_u32_e32 vcc, v26, v66
	v_addc_co_u32_e32 v251, vcc, 0, v251, vcc
	s_andn2_b64 vcc, exec, s[42:43]
	s_cbranch_vccz .LBB0_776

.LBB0_771:
	v_cmp_ge_u32_e32 vcc, v40, v66
	v_addc_co_u32_e32 v251, vcc, 0, v251, vcc
	v_cmp_ge_u32_e32 vcc, v36, v66
	v_addc_co_u32_e32 v251, vcc, 0, v251, vcc
	v_cmp_ge_u32_e32 vcc, v43, v66
	v_addc_co_u32_e32 v251, vcc, 0, v251, vcc
	v_cmp_ge_u32_e32 vcc, v42, v66
	v_addc_co_u32_e32 v251, vcc, 0, v251, vcc
	v_cmp_ge_u32_e32 vcc, v46, v66
	v_addc_co_u32_e32 v251, vcc, 0, v251, vcc
	v_cmp_ge_u32_e32 vcc, v45, v66
	v_addc_co_u32_e32 v251, vcc, 0, v251, vcc
	v_cmp_ge_u32_e32 vcc, v48, v66
	v_addc_co_u32_e32 v251, vcc, 0, v251, vcc
	v_cmp_ge_u32_e32 vcc, v47, v66
	v_addc_co_u32_e32 v251, vcc, 0, v251, vcc
	s_andn2_b64 vcc, exec, s[46:47]
	s_cbranch_vccz .LBB0_778

.LBB0_774:
	v_cmp_ge_u32_e32 vcc, v13, v66
	v_addc_co_u32_e32 v251, vcc, 0, v251, vcc
	v_cmp_ge_u32_e32 vcc, v12, v66
	v_addc_co_u32_e32 v251, vcc, 0, v251, vcc
	v_cmp_ge_u32_e32 vcc, v15, v66
	v_addc_co_u32_e32 v251, vcc, 0, v251, vcc
	v_cmp_ge_u32_e32 vcc, v14, v66
	v_addc_co_u32_e32 v251, vcc, 0, v251, vcc
	v_cmp_ge_u32_e32 vcc, v17, v66
	v_addc_co_u32_e32 v251, vcc, 0, v251, vcc
	v_cmp_ge_u32_e32 vcc, v16, v66
	v_addc_co_u32_e32 v251, vcc, 0, v251, vcc
	v_cmp_ge_u32_e32 vcc, v19, v66
	v_addc_co_u32_e32 v251, vcc, 0, v251, vcc
	v_cmp_ge_u32_e32 vcc, v18, v66
	v_addc_co_u32_e32 v251, vcc, 0, v251, vcc
	s_andn2_b64 vcc, exec, s[40:41]
	s_cbranch_vccz .LBB0_769

.LBB0_776:
	v_cmp_ge_u32_e32 vcc, v29, v66
	v_addc_co_u32_e32 v251, vcc, 0, v251, vcc
	v_cmp_ge_u32_e32 vcc, v28, v66
	v_addc_co_u32_e32 v251, vcc, 0, v251, vcc
	v_cmp_ge_u32_e32 vcc, v31, v66
	v_addc_co_u32_e32 v251, vcc, 0, v251, vcc
	v_cmp_ge_u32_e32 vcc, v30, v66
	v_addc_co_u32_e32 v251, vcc, 0, v251, vcc
	v_cmp_ge_u32_e32 vcc, v33, v66
	v_addc_co_u32_e32 v251, vcc, 0, v251, vcc
	v_cmp_ge_u32_e32 vcc, v32, v66
	v_addc_co_u32_e32 v251, vcc, 0, v251, vcc
	v_cmp_ge_u32_e32 vcc, v35, v66
	v_addc_co_u32_e32 v251, vcc, 0, v251, vcc
	v_cmp_ge_u32_e32 vcc, v34, v66
	v_addc_co_u32_e32 v251, vcc, 0, v251, vcc
	s_andn2_b64 vcc, exec, s[44:45]
	s_cbranch_vccz .LBB0_771

.LBB0_778:
	v_cmp_ge_u32_e32 vcc, v50, v66
	v_addc_co_u32_e32 v251, vcc, 0, v251, vcc
	v_cmp_ge_u32_e32 vcc, v49, v66
	v_addc_co_u32_e32 v251, vcc, 0, v251, vcc
	v_cmp_ge_u32_e32 vcc, v52, v66
	v_addc_co_u32_e32 v251, vcc, 0, v251, vcc
	v_cmp_ge_u32_e32 vcc, v51, v66
	v_addc_co_u32_e32 v251, vcc, 0, v251, vcc
	v_cmp_ge_u32_e32 vcc, v54, v66
	v_addc_co_u32_e32 v251, vcc, 0, v251, vcc
	v_cmp_ge_u32_e32 vcc, v53, v66
	v_addc_co_u32_e32 v251, vcc, 0, v251, vcc
	v_cmp_ge_u32_e32 vcc, v56, v66
	v_addc_co_u32_e32 v251, vcc, 0, v251, vcc
	v_cmp_ge_u32_e32 vcc, v55, v66
	v_addc_co_u32_e32 v251, vcc, 0, v251, vcc
	s_andn2_b64 vcc, exec, s[48:49]
	s_cbranch_vccnz .LBB0_765
.LBB0_779:
	v_cmp_ge_u32_e32 vcc, v58, v66
	v_addc_co_u32_e32 v251, vcc, 0, v251, vcc
	v_cmp_ge_u32_e32 vcc, v57, v66
	v_addc_co_u32_e32 v251, vcc, 0, v251, vcc
	v_cmp_ge_u32_e32 vcc, v60, v66
	v_addc_co_u32_e32 v251, vcc, 0, v251, vcc
	v_cmp_ge_u32_e32 vcc, v59, v66
	v_addc_co_u32_e32 v251, vcc, 0, v251, vcc
	v_cmp_ge_u32_e32 vcc, v62, v66
	v_addc_co_u32_e32 v251, vcc, 0, v251, vcc
	v_cmp_ge_u32_e32 vcc, v61, v66
	v_addc_co_u32_e32 v251, vcc, 0, v251, vcc
	v_cmp_ge_u32_e32 vcc, v64, v66
	v_addc_co_u32_e32 v251, vcc, 0, v251, vcc
	v_cmp_ge_u32_e32 vcc, v63, v66
	v_addc_co_u32_e32 v251, vcc, 0, v251, vcc
	s_branch .LBB0_765

.LBB0_884:
	s_or_b64 exec, exec, s[2:3]
	s_lshl_b32 s38, s58, 5
	v_readlane_b32 s42, v248, 6
	v_readfirstlane_b32 s2, v104
	v_readlane_b32 s43, v248, 7
	v_writelane_b32 v248, s38, 16
	s_lshr_b32 s2, s2, 3
	s_mov_b32 s43, s45
	v_readlane_b32 s41, v248, 12
	s_and_b32 s40, s2, 0x1ffffff8
	s_lshl_b64 s[2:3], s[42:43], 12
	s_mov_b32 s44, s42
	s_lshl_b64 s[42:43], s[42:43], 20
	s_lshl_b32 s39, s41, 19
	s_or_b32 s39, s42, s39
	s_or_b32 s42, s39, 0x800000
	s_lshl_b32 s39, s41, 14
	v_or_b32_e32 v0, s38, v125
	s_or_b32 s39, s39, s2
	s_mov_b32 s56, s47
	s_add_i32 s33, s40, s38
	v_or_b32_e32 v8, s2, v0
	v_mov_b32_e32 v9, s3
	v_readlane_b32 s48, v250, 0
	s_or_b32 s46, s39, 0x90000
	s_mov_b32 s47, s3
	v_lshlrev_b64 v[0:1], 9, v[8:9]
	v_readlane_b32 s52, v250, 4
	v_readlane_b32 s53, v250, 5
	v_or_b32_e32 v80, s33, v168
	s_lshl_b32 s33, s41, 16
	s_lshl_b64 s[46:47], s[46:47], 7
	v_lshl_add_u64 v[146:147], s[52:53], 0, v[0:1]
	v_add_u32_e32 v0, s33, v172
	v_lshl_add_u64 v[148:149], v[138:139], 0, s[46:47]
	s_movk_i32 s48, 0x1000
	v_readlane_b32 s49, v250, 1
	v_or_b32_e32 v8, s2, v0
	v_mov_b32_e32 v81, v117
	v_or_b32_e32 v76, 4, v80
	v_mov_b32_e32 v77, v117
	v_add_co_u32_e32 v24, vcc, s48, v148
	v_lshl_add_u64 v[0:1], v[8:9], 0, v[80:81]
	v_lshl_add_u64 v[8:9], v[8:9], 0, v[76:77]
	v_lshl_add_u64 v[150:151], v[136:137], 0, s[42:43]
	v_addc_co_u32_e32 v25, vcc, 0, v149, vcc
	s_mov_b32 s49, 0x40000
	v_lshlrev_b64 v[0:1], 7, v[0:1]
	v_lshlrev_b64 v[8:9], 7, v[8:9]
	v_add_co_u32_e32 v28, vcc, s49, v150
	v_lshl_add_u64 v[4:5], v[140:141], 0, v[0:1]
	v_lshl_add_u64 v[12:13], v[140:141], 0, v[8:9]
	v_addc_co_u32_e32 v29, vcc, 0, v151, vcc
	s_barrier
	global_load_dwordx4 v[0:3], v[4:5], off
	s_nop 0
	global_load_dwordx4 v[4:7], v[4:5], off offset:64
	s_nop 0
	global_load_dwordx4 v[8:11], v[12:13], off
	s_nop 0
	global_load_dwordx4 v[12:15], v[12:13], off offset:64
	s_nop 0
	global_load_dwordx4 v[16:19], v[148:149], off
	global_load_dwordx4 v[20:23], v[150:151], off
	s_lshr_b32 s38, s58, 1
	global_load_dwordx4 v[24:27], v[24:25], off
	s_nop 0
	global_load_dwordx4 v[28:31], v[28:29], off
	s_nop 0
	global_load_dwordx2 v[32:33], v[146:147], off
	s_cmpk_lt_u32 s56, 0xfc
	s_cselect_b64 s[42:43], -1, 0
	s_and_b64 s[46:47], s[42:43], exec
	v_writelane_b32 v248, s44, 6
	s_cselect_b32 s41, 64, 0
	v_mov_b32_e32 v40, 0
	v_writelane_b32 v248, s45, 7
	s_lshl_b32 s44, s41, 1
	s_mov_b32 s39, 0
	v_lshl_or_b32 v78, s40, 3, v170
	s_add_i32 s40, s38, 1
	v_mov_b32_e32 v41, v40
	v_mov_b32_e32 v42, v40
	v_mov_b32_e32 v43, v40
	v_mov_b32_e32 v44, v40
	v_mov_b32_e32 v45, v40
	v_mov_b32_e32 v46, v40
	v_mov_b32_e32 v47, v40
	v_mov_b32_e32 v52, v40
	v_mov_b32_e32 v53, v40
	v_mov_b32_e32 v54, v40
	v_mov_b32_e32 v55, v40
	v_mov_b32_e32 v34, v40
	v_mov_b32_e32 v35, v40
	v_mov_b32_e32 v48, v40
	v_mov_b32_e32 v49, v40
	s_waitcnt vmcnt(7)
	s_waitcnt vmcnt(5)
	s_waitcnt vmcnt(4)
	ds_write_b128 v127, v[16:19]
	s_waitcnt vmcnt(3)
	ds_write_b128 v127, v[20:23] offset:18432
	s_waitcnt vmcnt(2)
	ds_write_b128 v127, v[24:27] offset:4608
	s_waitcnt vmcnt(1)
	ds_write_b128 v127, v[28:31] offset:23040
	s_waitcnt vmcnt(0)
	ds_write_b64 v169, v[32:33] offset:53376
	v_lshl_add_u64 v[28:29], v[150:151], 0, s[44:45]
	s_lshl_b32 s44, s41, 7
	v_lshl_add_u64 v[24:25], v[148:149], 0, s[44:45]
	global_load_dwordx4 v[16:19], v[24:25], off
	global_load_dwordx4 v[20:23], v[28:29], off
	v_add_co_u32_e32 v24, vcc, s48, v24
	v_cndmask_b32_e64 v32, 0, 1, s[42:43]
	s_nop 0
	v_addc_co_u32_e32 v25, vcc, 0, v25, vcc
	v_add_co_u32_e32 v28, vcc, s49, v28
	v_lshlrev_b32_e32 v32, 3, v32
	v_mov_b32_e32 v33, v117
	v_addc_co_u32_e32 v29, vcc, 0, v29, vcc
	v_lshl_add_u64 v[32:33], v[146:147], 0, v[32:33]
	global_load_dwordx4 v[24:27], v[24:25], off
	v_mov_b32_e32 v50, v40
	global_load_dwordx4 v[28:31], v[28:29], off
	v_mov_b32_e32 v51, v40
	global_load_dwordx2 v[152:153], v[32:33], off
	v_mov_b32_e32 v32, v40
	v_mov_b32_e32 v33, v40
	v_mov_b32_e32 v56, v40
	v_mov_b32_e32 v57, v40
	v_mov_b32_e32 v58, v40
	v_mov_b32_e32 v59, v40
	v_mov_b32_e32 v60, v40
	v_mov_b32_e32 v61, v40
	v_mov_b32_e32 v62, v40
	v_mov_b32_e32 v63, v40
	v_mov_b32_e32 v36, v40
	v_mov_b32_e32 v37, v40
	v_mov_b32_e32 v38, v40
	v_mov_b32_e32 v39, v40
	v_mov_b32_e32 v154, v40
	v_mov_b32_e32 v155, v40
	v_readlane_b32 s50, v250, 2
	v_readlane_b32 s51, v250, 3
	v_readlane_b32 s54, v250, 6
	v_readlane_b32 s55, v250, 7
	v_lshlrev_b32_e32 v199, 4, v104
	ds_write_b128 v199, v[84:87] offset:54016
	s_waitcnt lgkmcnt(0)
	s_barrier
.LBB0_885:
	s_and_b32 s41, s39, 1
	s_xor_b32 s42, s41, 1
	s_mul_i32 s43, s42, 0x2400
	v_add_u32_e32 v199, s43, v127
	s_waitcnt vmcnt(4)
	ds_write_b128 v199, v[16:19]
	s_waitcnt vmcnt(3)
	ds_write_b128 v199, v[20:23] offset:18432
	s_waitcnt vmcnt(1)
	ds_write_b128 v199, v[24:27] offset:4608
	s_waitcnt vmcnt(0)
	ds_write_b128 v199, v[28:31] offset:23040
	v_lshl_or_b32 v217, s42, 8, v169
	ds_write_b64 v217, v[152:153] offset:53376
	v_lshl_add_u32 v217, s41, 8, v78
	s_mulk_i32 s41, 0x2400
	v_add_u32_e32 v251, s41, v129
	v_add_u32_e32 v199, s41, v131
	ds_read_b64 v[212:213], v217 offset:53376
	ds_read_b64 v[246:247], v217 offset:53408
	ds_read_b128 v[218:221], v251 offset:0
	ds_read_b128 v[222:225], v251 offset:64
	ds_read_b128 v[226:229], v251 offset:2304
	ds_read_b128 v[230:233], v251 offset:2368
	ds_read_b128 v[234:237], v251 offset:4608
	ds_read_b128 v[238:241], v251 offset:4672
	ds_read_b128 v[242:245], v251 offset:6912
	ds_read_b128 v[200:203], v251 offset:6976
	s_add_i32 s42, s39, 2
	s_min_i32 s42, s42, s38
	s_lshl_b32 s44, s42, 13
	s_lshl_b32 s46, s42, 7
	s_mov_b32 s47, s45
	s_mov_b32 s43, s45
	v_lshl_add_u64 v[16:17], v[148:149], 0, s[44:45]
	v_lshl_add_u64 v[28:29], v[150:151], 0, s[46:47]
	v_lshl_add_u64 v[152:153], s[42:43], 3, v[146:147]
	global_load_dwordx4 v[16:19], v[16:17], off
	global_load_dwordx4 v[20:23], v[28:29], off
	global_load_dwordx2 v[152:153], v[152:153], off
	s_addk_i32 s44, 0x1000
	s_add_i32 s46, s46, 0x40000
	v_lshl_add_u64 v[24:25], v[148:149], 0, s[44:45]
	v_lshl_add_u64 v[28:29], v[150:151], 0, s[46:47]
	global_load_dwordx4 v[24:27], v[24:25], off
	global_load_dwordx4 v[28:31], v[28:29], off
	s_waitcnt lgkmcnt(8)
	v_lshrrev_b32_e32 v212, v112, v212
	v_lshrrev_b32_e32 v213, v112, v213
	v_lshrrev_b32_e32 v246, v112, v246
	v_lshrrev_b32_e32 v247, v112, v247
	s_waitcnt lgkmcnt(7)
	v_mfma_f32_16x16x32_bf16 v[64:67], v[218:221], v[0:3], 0
	v_mfma_f32_16x16x32_bf16 v[68:71], v[218:221], v[8:11], 0
	ds_read_b64 v[194:195], v199 offset:18432
	ds_read_b64 v[196:197], v199 offset:18464
	s_waitcnt lgkmcnt(8)
	v_mfma_f32_16x16x32_bf16 v[64:67], v[222:225], v[4:7], v[64:67]
	v_mfma_f32_16x16x32_bf16 v[68:71], v[222:225], v[12:15], v[68:71]
	s_waitcnt lgkmcnt(7)
	v_mfma_f32_16x16x32_bf16 v[72:75], v[226:229], v[0:3], 0
	v_mfma_f32_16x16x32_bf16 v[156:159], v[226:229], v[8:11], 0
	ds_read_b64 v[204:205], v199 offset:20736
	ds_read_b64 v[206:207], v199 offset:20768
	s_waitcnt lgkmcnt(8)
	v_mfma_f32_16x16x32_bf16 v[72:75], v[230:233], v[4:7], v[72:75]
	v_mfma_f32_16x16x32_bf16 v[156:159], v[230:233], v[12:15], v[156:159]
	s_waitcnt lgkmcnt(7)
	v_mfma_f32_16x16x32_bf16 v[160:163], v[234:237], v[0:3], 0
	v_mfma_f32_16x16x32_bf16 v[182:185], v[234:237], v[8:11], 0
	ds_read_b64 v[208:209], v199 offset:23040
	ds_read_b64 v[210:211], v199 offset:23072
	s_waitcnt lgkmcnt(8)
	v_mfma_f32_16x16x32_bf16 v[160:163], v[238:241], v[4:7], v[160:163]
	v_mfma_f32_16x16x32_bf16 v[182:185], v[238:241], v[12:15], v[182:185]
	ds_read_b64 v[218:219], v199 offset:18496
	ds_read_b64 v[220:221], v199 offset:18528
	ds_read_b64 v[222:223], v199 offset:20800
	ds_read_b64 v[224:225], v199 offset:20832
	s_waitcnt lgkmcnt(11)
	v_mfma_f32_16x16x32_bf16 v[186:189], v[242:245], v[0:3], 0
	v_mfma_f32_16x16x32_bf16 v[190:193], v[242:245], v[8:11], 0
	ds_read_b64 v[84:85], v199 offset:25344
	ds_read_b64 v[86:87], v199 offset:25376
	s_waitcnt lgkmcnt(12)
	v_mfma_f32_16x16x32_bf16 v[186:189], v[200:203], v[4:7], v[186:189]
	v_mfma_f32_16x16x32_bf16 v[190:193], v[200:203], v[12:15], v[190:193]
	ds_read_b64 v[226:227], v199 offset:23104
	ds_read_b64 v[228:229], v199 offset:23136
	ds_read_b64 v[230:231], v199 offset:25408
	s_waitcnt lgkmcnt(13)
	ds_read_b64 v[232:233], v199 offset:25440
	s_waitcnt lgkmcnt(0)
	s_barrier
	v_exp_f32_e32 v64, v64
	v_exp_f32_e32 v68, v68
	v_exp_f32_e32 v65, v65
	v_exp_f32_e32 v69, v69
	v_bfe_i32 v82, v212, 0, 1
	v_bfe_i32 v145, v246, 0, 1
	v_exp_f32_e32 v66, v66
	v_exp_f32_e32 v70, v70
	v_and_b32_e32 v64, v82, v64
	v_and_b32_e32 v68, v145, v68
	v_bfe_i32 v113, v212, 1, 1
	v_bfe_i32 v198, v246, 1, 1
	v_exp_f32_e32 v67, v67
	v_exp_f32_e32 v71, v71
	v_and_b32_e32 v65, v113, v65
	v_and_b32_e32 v69, v198, v69
	v_add_f32_e32 v155, v155, v64
	v_add_f32_e32 v154, v154, v68
	v_bfe_i32 v82, v212, 2, 1
	v_bfe_i32 v145, v246, 2, 1
	v_and_b32_e32 v66, v82, v66
	v_and_b32_e32 v70, v145, v70
	v_add_f32_e32 v155, v155, v65
	v_add_f32_e32 v154, v154, v69
	v_bfe_i32 v113, v212, 3, 1
	v_bfe_i32 v198, v246, 3, 1
	v_and_b32_e32 v67, v113, v67
	v_and_b32_e32 v71, v198, v71
	v_add_f32_e32 v155, v155, v66
	v_add_f32_e32 v154, v154, v70
	v_add_f32_e32 v155, v155, v67
	v_add_f32_e32 v154, v154, v71
	v_exp_f32_e32 v72, v72
	v_exp_f32_e32 v156, v156
	v_exp_f32_e32 v73, v73
	v_exp_f32_e32 v157, v157
	v_bfe_i32 v82, v212, 16, 1
	v_bfe_i32 v145, v246, 16, 1
	v_exp_f32_e32 v74, v74
	v_exp_f32_e32 v158, v158
	v_and_b32_e32 v72, v82, v72
	v_and_b32_e32 v156, v145, v156
	v_bfe_i32 v113, v212, 17, 1
	v_bfe_i32 v198, v246, 17, 1
	v_exp_f32_e32 v75, v75
	v_exp_f32_e32 v159, v159
	v_and_b32_e32 v73, v113, v73
	v_and_b32_e32 v157, v198, v157
	v_add_f32_e32 v155, v155, v72
	v_add_f32_e32 v154, v154, v156
	v_bfe_i32 v82, v212, 18, 1
	v_bfe_i32 v145, v246, 18, 1
	v_and_b32_e32 v74, v82, v74
	v_and_b32_e32 v158, v145, v158
	v_add_f32_e32 v155, v155, v73
	v_add_f32_e32 v154, v154, v157
	v_bfe_i32 v113, v212, 19, 1
	v_bfe_i32 v198, v246, 19, 1
	v_and_b32_e32 v75, v113, v75
	v_and_b32_e32 v159, v198, v159
	v_add_f32_e32 v155, v155, v74
	v_add_f32_e32 v154, v154, v158
	v_add_f32_e32 v155, v155, v75
	v_add_f32_e32 v154, v154, v159
	v_cvt_pk_bf16_f32 v64, v64, v65
	v_cvt_pk_bf16_f32 v68, v68, v69
	v_cvt_pk_bf16_f32 v65, v66, v67
	v_cvt_pk_bf16_f32 v69, v70, v71
	v_cvt_pk_bf16_f32 v66, v72, v73
	v_cvt_pk_bf16_f32 v70, v156, v157
	v_cvt_pk_bf16_f32 v67, v74, v75
	v_cvt_pk_bf16_f32 v71, v158, v159
	v_exp_f32_e32 v160, v160
	v_exp_f32_e32 v182, v182
	v_mfma_f32_16x16x32_bf16 v[36:39], v[194:197], v[64:67], v[36:39]
	v_exp_f32_e32 v161, v161
	v_exp_f32_e32 v183, v183
	v_bfe_i32 v82, v213, 0, 1
	v_bfe_i32 v145, v247, 0, 1
	v_exp_f32_e32 v162, v162
	v_exp_f32_e32 v184, v184
	v_and_b32_e32 v160, v82, v160
	v_and_b32_e32 v182, v145, v182
	v_bfe_i32 v113, v213, 1, 1
	v_mfma_f32_16x16x32_bf16 v[32:35], v[194:197], v[68:71], v[32:35]
	v_bfe_i32 v198, v247, 1, 1
	v_exp_f32_e32 v163, v163
	v_exp_f32_e32 v185, v185
	v_and_b32_e32 v161, v113, v161
	v_and_b32_e32 v183, v198, v183
	v_add_f32_e32 v155, v155, v160
	v_add_f32_e32 v154, v154, v182
	v_bfe_i32 v82, v213, 2, 1
	v_bfe_i32 v145, v247, 2, 1
	v_mfma_f32_16x16x32_bf16 v[60:63], v[204:207], v[64:67], v[60:63]
	v_and_b32_e32 v162, v82, v162
	v_and_b32_e32 v184, v145, v184
	v_add_f32_e32 v155, v155, v161
	v_add_f32_e32 v154, v154, v183
	v_bfe_i32 v113, v213, 3, 1
	v_bfe_i32 v198, v247, 3, 1
	v_and_b32_e32 v163, v113, v163
	v_and_b32_e32 v185, v198, v185
	v_add_f32_e32 v155, v155, v162
	v_mfma_f32_16x16x32_bf16 v[52:55], v[204:207], v[68:71], v[52:55]
	v_add_f32_e32 v154, v154, v184
	v_add_f32_e32 v155, v155, v163
	v_add_f32_e32 v154, v154, v185
	v_exp_f32_e32 v186, v186
	v_exp_f32_e32 v190, v190
	v_exp_f32_e32 v187, v187
	v_exp_f32_e32 v191, v191
	v_bfe_i32 v82, v213, 16, 1
	v_bfe_i32 v145, v247, 16, 1
	v_mfma_f32_16x16x32_bf16 v[56:59], v[208:211], v[64:67], v[56:59]
	v_exp_f32_e32 v188, v188
	v_exp_f32_e32 v192, v192
	v_and_b32_e32 v186, v82, v186
	v_and_b32_e32 v190, v145, v190
	v_bfe_i32 v113, v213, 17, 1
	v_bfe_i32 v198, v247, 17, 1
	v_exp_f32_e32 v189, v189
	v_exp_f32_e32 v193, v193
	v_and_b32_e32 v187, v113, v187
	v_mfma_f32_16x16x32_bf16 v[44:47], v[208:211], v[68:71], v[44:47]
	v_and_b32_e32 v191, v198, v191
	v_add_f32_e32 v155, v155, v186
	v_add_f32_e32 v154, v154, v190
	v_bfe_i32 v82, v213, 18, 1
	v_bfe_i32 v145, v247, 18, 1
	v_and_b32_e32 v188, v82, v188
	v_and_b32_e32 v192, v145, v192
	v_add_f32_e32 v155, v155, v187
	v_add_f32_e32 v154, v154, v191
	v_mfma_f32_16x16x32_bf16 v[48:51], v[84:87], v[64:67], v[48:51]
	v_bfe_i32 v113, v213, 19, 1
	v_bfe_i32 v198, v247, 19, 1
	v_and_b32_e32 v189, v113, v189
	v_and_b32_e32 v193, v198, v193
	v_add_f32_e32 v155, v155, v188
	v_add_f32_e32 v154, v154, v192
	v_add_f32_e32 v155, v155, v189
	v_add_f32_e32 v154, v154, v193
	v_cvt_pk_bf16_f32 v160, v160, v161
	v_mfma_f32_16x16x32_bf16 v[40:43], v[84:87], v[68:71], v[40:43]
	v_cvt_pk_bf16_f32 v182, v182, v183
	v_cvt_pk_bf16_f32 v161, v162, v163
	v_cvt_pk_bf16_f32 v183, v184, v185
	v_cvt_pk_bf16_f32 v162, v186, v187
	v_cvt_pk_bf16_f32 v184, v190, v191
	v_cvt_pk_bf16_f32 v163, v188, v189
	v_cvt_pk_bf16_f32 v185, v192, v193
	s_add_i32 s39, s39, 1
	s_nop 0
	v_mfma_f32_16x16x32_bf16 v[36:39], v[218:221], v[160:163], v[36:39]
	v_mfma_f32_16x16x32_bf16 v[32:35], v[218:221], v[182:185], v[32:35]
	v_mfma_f32_16x16x32_bf16 v[60:63], v[222:225], v[160:163], v[60:63]
	v_mfma_f32_16x16x32_bf16 v[52:55], v[222:225], v[182:185], v[52:55]
	v_mfma_f32_16x16x32_bf16 v[56:59], v[226:229], v[160:163], v[56:59]
	v_mfma_f32_16x16x32_bf16 v[44:47], v[226:229], v[182:185], v[44:47]
	v_mfma_f32_16x16x32_bf16 v[48:51], v[230:233], v[160:163], v[48:51]
	v_mfma_f32_16x16x32_bf16 v[40:43], v[230:233], v[182:185], v[40:43]
	s_cmp_lg_u32 s40, s39
	s_cbranch_scc1 .LBB0_885
	v_lshlrev_b32_e32 v199, 4, v104
	ds_read_b128 v[84:87], v199 offset:54016
	s_waitcnt lgkmcnt(0)
	v_add_u32_e32 v0, s33, v171
	v_or_b32_e32 v0, s2, v0
	v_mov_b32_e32 v1, s3
	v_lshl_add_u64 v[2:3], v[0:1], 0, v[80:81]
	v_lshlrev_b64 v[2:3], 7, v[2:3]
	v_lshl_add_u64 v[2:3], v[142:143], 0, v[2:3]
	global_load_dwordx2 v[4:5], v[2:3], off
	global_load_dwordx2 v[6:7], v[2:3], off offset:32
	global_load_dwordx2 v[8:9], v[2:3], off offset:64
	v_and_b32_e32 v15, 64, v121
	global_load_dwordx2 v[2:3], v[2:3], off offset:96
	v_xor_b32_e32 v14, 16, v121
	v_add_u32_e32 v15, 64, v15
	v_cmp_lt_i32_e32 vcc, v14, v15
	s_waitcnt vmcnt(8)
	v_xor_b32_e32 v16, 32, v121
	v_lshl_add_u64 v[0:1], v[0:1], 0, v[76:77]
	v_cndmask_b32_e32 v14, v121, v14, vcc
	s_waitcnt vmcnt(7)
	v_lshlrev_b32_e32 v20, 2, v14
	ds_bpermute_b32 v14, v20, v155
	v_cmp_lt_i32_e32 vcc, v16, v15
	v_lshlrev_b64 v[0:1], 7, v[0:1]
	v_lshl_add_u64 v[0:1], v[142:143], 0, v[0:1]
	v_cndmask_b32_e32 v15, v121, v16, vcc
	v_lshlrev_b32_e32 v21, 2, v15
	s_waitcnt lgkmcnt(0)
	v_add_f32_e32 v14, v155, v14
	ds_bpermute_b32 v15, v21, v14
	v_readlane_b32 s48, v250, 24
	v_add_u32_e32 v10, s2, v80
	v_mov_b32_e32 v11, v117
	v_readlane_b32 s49, v250, 25
	s_waitcnt lgkmcnt(0)
	v_add_f32_e32 v22, v14, v15
	global_load_dwordx2 v[14:15], v[0:1], off
	global_load_dwordx2 v[16:17], v[0:1], off offset:32
	global_load_dwordx2 v[18:19], v[0:1], off offset:64
	s_nop 0
	global_load_dwordx2 v[0:1], v[0:1], off offset:96
	v_div_scale_f32 v23, s[38:39], v22, v22, 1.0
	s_waitcnt vmcnt(9)
	v_rcp_f32_e32 v24, v23
	v_div_scale_f32 v25, vcc, 1.0, v22, 1.0
	v_readlane_b32 s60, v250, 36
	v_fma_f32 v26, -v23, v24, 1.0
	v_fmac_f32_e32 v24, v26, v24
	v_mul_f32_e32 v26, v25, v24
	v_fma_f32 v27, -v23, v26, v25
	v_fmac_f32_e32 v26, v27, v24
	v_fma_f32 v23, -v23, v26, v25
	v_div_fmas_f32 v23, v23, v24, v26
	v_readlane_b32 s61, v250, 37
	v_div_fixup_f32 v23, v23, v22, 1.0
	v_cmp_lt_f32_e32 vcc, 0, v22
	v_readlane_b32 s3, v248, 12
	v_lshlrev_b64 v[10:11], 11, v[10:11]
	s_mov_b64 s[48:49], s[60:61]
	v_cndmask_b32_e32 v22, 0, v23, vcc
	v_lshl_or_b32 v12, s3, 9, v179
	v_mov_b32_e32 v13, v117
	v_lshl_add_u64 v[10:11], s[48:49], 0, v[10:11]
	v_mul_f32_e32 v23, v36, v22
	v_mul_f32_e32 v24, v37, v22
	v_mul_f32_e32 v26, v39, v22
	v_mov_b32_e32 v145, v117
	v_lshl_add_u64 v[10:11], v[10:11], 0, v[12:13]
	v_mul_f32_e32 v25, v38, v22
	s_waitcnt vmcnt(8)
	v_mul_f32_e32 v28, v61, v22
	v_mul_f32_e32 v30, v63, v22
	v_lshl_add_u64 v[10:11], v[10:11], 0, v[144:145]
	v_mul_f32_e32 v27, v60, v22
	v_mul_f32_e32 v29, v62, v22
	v_mul_f32_e32 v31, v56, v22
	v_readlane_b32 s50, v250, 26
	v_readlane_b32 s51, v250, 27
	v_readlane_b32 s60, v250, 56
	v_readlane_b32 s61, v250, 57
	v_readlane_b32 s50, v248, 20
	v_readlane_b32 s51, v248, 21
	v_readlane_b32 s52, v250, 28
	v_readlane_b32 s53, v250, 29
	v_readlane_b32 s54, v250, 30
	v_readlane_b32 s55, v250, 31
	v_readlane_b32 s56, v250, 32
	v_readlane_b32 s57, v250, 33
	v_readlane_b32 s58, v250, 34
	v_readlane_b32 s59, v250, 35
	v_readlane_b32 s62, v250, 38
	v_readlane_b32 s63, v250, 39
	s_waitcnt vmcnt(7)
	v_lshlrev_b32_e32 v36, 16, v4
	v_and_b32_e32 v4, 0xffff0000, v4
	v_lshlrev_b32_e32 v37, 16, v5
	v_and_b32_e32 v5, 0xffff0000, v5
	s_waitcnt vmcnt(6)
	v_lshlrev_b32_e32 v38, 16, v6
	v_and_b32_e32 v6, 0xffff0000, v6
	v_lshlrev_b32_e32 v39, 16, v7
	v_and_b32_e32 v7, 0xffff0000, v7
	v_mul_f32_e32 v4, v24, v4
	v_mul_f32_e32 v5, v26, v5
	v_mul_f32_e32 v23, v23, v36
	v_mul_f32_e32 v24, v25, v37
	v_mul_f32_e32 v6, v28, v6
	v_mul_f32_e32 v7, v30, v7
	v_cvt_pk_bf16_f32 v4, v23, v4
	v_cvt_pk_bf16_f32 v5, v24, v5
	v_mul_f32_e32 v25, v27, v38
	v_mul_f32_e32 v26, v29, v39
	v_cvt_pk_bf16_f32 v6, v25, v6
	v_cvt_pk_bf16_f32 v7, v26, v7
	global_store_dwordx2 v[10:11], v[4:5], off offset:1024 sc1
	global_store_dwordx2 v[10:11], v[6:7], off offset:1056 sc1
	v_mul_f32_e32 v4, v57, v22
	s_waitcnt vmcnt(7)
	v_and_b32_e32 v5, 0xffff0000, v8
	v_mul_f32_e32 v4, v4, v5
	v_mul_f32_e32 v5, v58, v22
	v_lshlrev_b32_e32 v6, 16, v9
	v_mul_f32_e32 v5, v5, v6
	v_mul_f32_e32 v6, v59, v22
	v_and_b32_e32 v7, 0xffff0000, v9
	v_mul_f32_e32 v6, v6, v7
	v_cvt_pk_bf16_f32 v5, v5, v6
	ds_bpermute_b32 v6, v20, v154
	v_lshlrev_b32_e32 v56, 16, v8
	v_mul_f32_e32 v27, v31, v56
	v_cvt_pk_bf16_f32 v4, v27, v4
	global_store_dwordx2 v[10:11], v[4:5], off offset:1088 sc1
	v_mul_f32_e32 v4, v48, v22
	s_waitcnt vmcnt(7)
	v_lshlrev_b32_e32 v5, 16, v2
	v_mul_f32_e32 v4, v4, v5
	v_mul_f32_e32 v5, v49, v22
	v_and_b32_e32 v2, 0xffff0000, v2
	v_mul_f32_e32 v2, v5, v2
	s_waitcnt lgkmcnt(0)
	v_add_f32_e32 v5, v154, v6
	ds_bpermute_b32 v6, v21, v5
	v_cvt_pk_bf16_f32 v2, v4, v2
	v_mul_f32_e32 v4, v50, v22
	v_lshlrev_b32_e32 v7, 16, v3
	v_mul_f32_e32 v4, v4, v7
	s_waitcnt lgkmcnt(0)
	v_add_f32_e32 v5, v5, v6
	v_div_scale_f32 v6, s[38:39], v5, v5, 1.0
	v_rcp_f32_e32 v8, v6
	v_mul_f32_e32 v7, v51, v22
	v_and_b32_e32 v3, 0xffff0000, v3
	v_mul_f32_e32 v3, v7, v3
	v_cvt_pk_bf16_f32 v3, v4, v3
	global_store_dwordx2 v[10:11], v[2:3], off offset:1120 sc1
	v_fma_f32 v2, -v6, v8, 1.0
	v_fmac_f32_e32 v8, v2, v8
	v_div_scale_f32 v2, vcc, 1.0, v5, 1.0
	v_mul_f32_e32 v3, v2, v8
	v_fma_f32 v4, -v6, v3, v2
	v_fmac_f32_e32 v3, v4, v8
	v_fma_f32 v2, -v6, v3, v2
	v_div_fmas_f32 v2, v2, v8, v3
	v_div_fixup_f32 v2, v2, v5, 1.0
	v_cmp_lt_f32_e32 vcc, 0, v5
	s_waitcnt vmcnt(7)
	v_lshlrev_b32_e32 v5, 16, v14
	v_mov_b32_e32 v3, v117
	v_cndmask_b32_e32 v6, 0, v2, vcc
	v_mul_f32_e32 v4, v32, v6
	v_add_u32_e32 v2, s2, v76
	v_mul_f32_e32 v4, v4, v5
	v_mul_f32_e32 v5, v33, v6
	v_and_b32_e32 v7, 0xffff0000, v14
	v_lshlrev_b64 v[2:3], 11, v[2:3]
	v_mul_f32_e32 v5, v5, v7
	v_lshl_add_u64 v[2:3], s[48:49], 0, v[2:3]
	v_cvt_pk_bf16_f32 v4, v4, v5
	v_mul_f32_e32 v5, v34, v6
	v_lshlrev_b32_e32 v7, 16, v15
	v_lshl_add_u64 v[2:3], v[2:3], 0, v[12:13]
	v_mul_f32_e32 v5, v5, v7
	v_mul_f32_e32 v7, v35, v6
	v_and_b32_e32 v8, 0xffff0000, v15
	v_lshl_add_u64 v[2:3], v[2:3], 0, v[144:145]
	v_mul_f32_e32 v7, v7, v8
	v_cvt_pk_bf16_f32 v5, v5, v7
	global_store_dwordx2 v[2:3], v[4:5], off offset:1024 sc1
	v_mul_f32_e32 v4, v52, v6
	s_waitcnt vmcnt(7)
	v_lshlrev_b32_e32 v5, 16, v16
	v_mul_f32_e32 v4, v4, v5
	v_mul_f32_e32 v5, v53, v6
	v_and_b32_e32 v7, 0xffff0000, v16
	v_mul_f32_e32 v5, v5, v7
	v_cvt_pk_bf16_f32 v4, v4, v5
	v_mul_f32_e32 v5, v54, v6
	v_lshlrev_b32_e32 v7, 16, v17
	v_mul_f32_e32 v5, v5, v7
	v_mul_f32_e32 v7, v55, v6
	v_and_b32_e32 v8, 0xffff0000, v17
	v_mul_f32_e32 v7, v7, v8
	v_cvt_pk_bf16_f32 v5, v5, v7
	global_store_dwordx2 v[2:3], v[4:5], off offset:1056 sc1
	v_mul_f32_e32 v4, v44, v6
	s_waitcnt vmcnt(7)
	v_lshlrev_b32_e32 v5, 16, v18
	v_mul_f32_e32 v4, v4, v5
	v_mul_f32_e32 v5, v45, v6
	v_and_b32_e32 v7, 0xffff0000, v18
	v_mul_f32_e32 v5, v5, v7
	v_cvt_pk_bf16_f32 v4, v4, v5
	v_mul_f32_e32 v5, v46, v6
	v_lshlrev_b32_e32 v7, 16, v19
	v_mul_f32_e32 v5, v5, v7
	v_mul_f32_e32 v7, v47, v6
	v_and_b32_e32 v8, 0xffff0000, v19
	v_mul_f32_e32 v7, v7, v8
	v_cvt_pk_bf16_f32 v5, v5, v7
	global_store_dwordx2 v[2:3], v[4:5], off offset:1088 sc1
	v_mul_f32_e32 v4, v40, v6
	s_waitcnt vmcnt(7)
	v_lshlrev_b32_e32 v5, 16, v0
	v_mul_f32_e32 v4, v4, v5
	v_mul_f32_e32 v5, v41, v6
	v_and_b32_e32 v0, 0xffff0000, v0
	v_mul_f32_e32 v0, v5, v0
	v_cvt_pk_bf16_f32 v0, v4, v0
	v_mul_f32_e32 v4, v42, v6
	v_lshlrev_b32_e32 v5, 16, v1
	v_mul_f32_e32 v4, v4, v5
	v_mul_f32_e32 v5, v43, v6
	v_and_b32_e32 v1, 0xffff0000, v1
	v_mul_f32_e32 v1, v5, v1
	v_cvt_pk_bf16_f32 v1, v4, v1
	global_store_dwordx2 v[2:3], v[0:1], off offset:1120 sc1
	s_waitcnt vmcnt(0)
	s_mov_b64 s[2:3], s[60:61]
	s_barrier

	.amdhsa_kernel _Z4mega6Params
		.amdhsa_group_segment_fixed_size 73744
		.amdhsa_private_segment_fixed_size 0
		.amdhsa_kernarg_size 552
		.amdhsa_user_sgpr_count 2
		.amdhsa_user_sgpr_dispatch_ptr 0
		.amdhsa_user_sgpr_queue_ptr 0
		.amdhsa_user_sgpr_kernarg_segment_ptr 1
		.amdhsa_user_sgpr_dispatch_id 0
		.amdhsa_user_sgpr_kernarg_preload_length 0
		.amdhsa_user_sgpr_kernarg_preload_offset 0
		.amdhsa_user_sgpr_private_segment_size 0
		.amdhsa_uses_dynamic_stack 0
		.amdhsa_enable_private_segment 0
		.amdhsa_system_sgpr_workgroup_id_x 1
		.amdhsa_system_sgpr_workgroup_id_y 0
		.amdhsa_system_sgpr_workgroup_id_z 0
		.amdhsa_system_sgpr_workgroup_info 0
		.amdhsa_system_vgpr_workitem_id 2
		.amdhsa_next_free_vgpr 256
		.amdhsa_next_free_sgpr 100
		.amdhsa_accum_offset 256
		.amdhsa_reserve_vcc 1
		.amdhsa_float_round_mode_32 0
		.amdhsa_float_round_mode_16_64 0
		.amdhsa_float_denorm_mode_32 3
		.amdhsa_float_denorm_mode_16_64 3
		.amdhsa_dx10_clamp 1
		.amdhsa_ieee_mode 1
		.amdhsa_fp16_overflow 0
		.amdhsa_tg_split 0
		.amdhsa_exception_fp_ieee_invalid_op 0
		.amdhsa_exception_fp_denorm_src 0
		.amdhsa_exception_fp_ieee_div_zero 0
		.amdhsa_exception_fp_ieee_overflow 0
		.amdhsa_exception_fp_ieee_underflow 0
		.amdhsa_exception_fp_ieee_inexact 0
		.amdhsa_exception_int_div_zero 0
	.end_amdhsa_kernel

amdhsa.kernels:
  - .agpr_count:     0
    .args:
      - .offset:         0
        .size:           296
        .value_kind:     by_value
      - .offset:         296
        .size:           4
        .value_kind:     hidden_block_count_x
      - .offset:         300
        .size:           4
        .value_kind:     hidden_block_count_y
      - .offset:         304
        .size:           4
        .value_kind:     hidden_block_count_z
      - .offset:         308
        .size:           2
        .value_kind:     hidden_group_size_x
      - .offset:         310
        .size:           2
        .value_kind:     hidden_group_size_y
      - .offset:         312
        .size:           2
        .value_kind:     hidden_group_size_z
      - .offset:         314
        .size:           2
        .value_kind:     hidden_remainder_x
      - .offset:         316
        .size:           2
        .value_kind:     hidden_remainder_y
      - .offset:         318
        .size:           2
        .value_kind:     hidden_remainder_z
      - .offset:         336
        .size:           8
        .value_kind:     hidden_global_offset_x
      - .offset:         344
        .size:           8
        .value_kind:     hidden_global_offset_y
      - .offset:         352
        .size:           8
        .value_kind:     hidden_global_offset_z
      - .offset:         360
        .size:           2
        .value_kind:     hidden_grid_dims
      - .offset:         384
        .size:           8
        .value_kind:     hidden_multigrid_sync_arg
    .group_segment_fixed_size: 73744
    .kernarg_segment_align: 8
    .kernarg_segment_size: 552
    .language:       OpenCL C
    .language_version:
      - 2
      - 0
    .max_flat_workgroup_size: 256
    .name:           _Z4mega6Params
    .private_segment_fixed_size: 0
    .sgpr_count:     106
    .sgpr_spill_count: 234
    .symbol:         _Z4mega6Params.kd
    .uniform_work_group_size: 1
    .uses_dynamic_stack: false
    .vgpr_count:     256
    .vgpr_spill_count: 0
    .wavefront_size: 64
